# v52 + phase-2 LDS-address v_add_u32 hoisted to K-loop pre-headers (18 of 20 in-loop loader VALU now gone in 4 loops)
# speedup vs baseline: 1.0054x; 1.0002x over previous
; #define PG8_BAR __builtin_amdgcn_s_barrier()
; template <class Epi, class Sched, class GemmT>
; __device__ __forceinline__ void gemm_phase(LAS unsigned char* lds, const GemmT& g, const Sched& S, const Epi& E, const int wid) {
;     ...
;     Acc acc;
; #pragma unroll
;     for (int a = 0; a < 2; ++a)
; #pragma unroll
;         for (int b = 0; b < 2; ++b)
; #pragma unroll
;             for (int m = 0; m < 4; ++m)
; #pragma unroll
;                 for (int n = 0; n < 2; ++n) acc[a][b][m][n] = (f32x4){0.f, 0.f, 0.f, 0.f};
;     bf16x8 At[4][2], B0[2][2], B1[2][2];
;     const int sc8 = 0x7f7f7f7f; (void)sc8;
;     Seg cs = g.seg(cur, 0);
;     unsigned voffA[2], voffB[2]; size_t hstepA, hstepB;
;     PG8_VOFFS(voffA, voffB, hstepA, hstepB, cs);
;     const char* cA = cs.A; const char* cB = cs.B;
;     PG8_STAGE(PG8_SB(0, 0), cB, voffB); PG8_STAGE(PG8_SB(0, 1), cB + hstepB, voffB); PG8_STAGE(PG8_SA(0, 0), cA, voffA); PG8_STAGE(PG8_SA(0, 1), cA + hstepA, voffA);
;     if (wr == 1) PG8_BAR;
;     PG8_WAIT_V(2); PG8_BAR;
;     PG8_STAGE(PG8_SB(1, 0), cB + kstep, voffB); PG8_STAGE(PG8_SA(1, 0), cA + kstep, voffA); PG8_STAGE(PG8_SB(1, 1), cB + hstepB + kstep, voffB);
;     PG8_WAIT_V(6); PG8_BAR;
;     for (;;) {
;         const bool has_next = S.next(ui + 1, nxt);
; #pragma unroll 1
;         for (int sgi = 0; sgi < NSEG; ++sgi) {
;             const Seg ns = (sgi + 1 < NSEG) ? g.seg(cur, sgi + 1) : g.seg(has_next ? nxt : cur, 0);
;             unsigned nvA[2], nvB[2]; size_t nhA, nhB;
;             if constexpr (GemmT::UNIFORM) { nvA[0] = voffA[0]; nvA[1] = voffA[1]; nvB[0] = voffB[0]; nvB[1] = voffB[1]; nhA = hstepA; nhB = hstepB; }
;             else PG8_VOFFS(nvA, nvB, nhA, nhB, ns);
;             const int nt = cs.nt;
;             for (int t = 0; t < nt; t += 2) {
;                 const bool last = (t == nt - 2);
;                 const char* a1 = cA + (size_t)(t + 1) * kstep;
;                 const char* a2 = last ? ns.A : cA + (size_t)(t + 2) * kstep; const char* b2 = last ? ns.B : cB + (size_t)(t + 2) * kstep;
;                 const char* a3 = a2 + kstep; const char* b3 = b2 + kstep;
;                 unsigned vA2[2], vB2[2];
; #pragma unroll
;                 for (int i = 0; i < 2; ++i) { vA2[i] = last ? nvA[i] : voffA[i]; vB2[i] = last ? nvB[i] : voffB[i]; }
;                 const size_t hA2 = last ? nhA : hstepA, hB2 = last ? nhB : hstepB;
.LBB0_360:
	s_ashr_i32 s71, s70, 31
	s_ashr_i32 s45, s44, 31
	s_lshl_b64 s[36:37], s[70:71], 20
	s_add_u32 s42, s8, s36
	s_addc_u32 s43, s9, s37
	s_lshl_b64 s[44:45], s[44:45], 20
	s_add_u32 s36, s6, s44
	s_addc_u32 s37, s7, s45
	s_add_u32 s56, s56, 0x80080
	s_addc_u32 s57, s57, 0
	s_add_u32 s38, s62, s58
	v_mov_b32_e32 v32, 0
	s_addc_u32 s39, s63, s59
	s_mov_b32 s40, -2
	v_mov_b32_e32 v33, v32
	v_mov_b32_e32 v34, v32
	v_mov_b32_e32 v35, v32
	v_mov_b32_e32 v36, v32
	v_mov_b32_e32 v37, v32
	v_mov_b32_e32 v38, v32
	v_mov_b32_e32 v39, v32
	v_mov_b32_e32 v48, v32
	v_mov_b32_e32 v49, v32
	v_mov_b32_e32 v50, v32
	v_mov_b32_e32 v51, v32
	v_mov_b32_e32 v52, v32
	v_mov_b32_e32 v53, v32
	v_mov_b32_e32 v54, v32
	v_mov_b32_e32 v55, v32
	v_mov_b32_e32 v64, v32
	v_mov_b32_e32 v65, v32
	v_mov_b32_e32 v66, v32
	v_mov_b32_e32 v67, v32
	v_mov_b32_e32 v68, v32
	v_mov_b32_e32 v69, v32
	v_mov_b32_e32 v70, v32
	v_mov_b32_e32 v71, v32
	v_mov_b32_e32 v80, v32
	v_mov_b32_e32 v81, v32
	v_mov_b32_e32 v82, v32
	v_mov_b32_e32 v83, v32
	v_mov_b32_e32 v84, v32
	v_mov_b32_e32 v85, v32
	v_mov_b32_e32 v86, v32
	v_mov_b32_e32 v87, v32
	v_mov_b32_e32 v96, v32
	v_mov_b32_e32 v97, v32
	v_mov_b32_e32 v98, v32
	v_mov_b32_e32 v99, v32
	v_mov_b32_e32 v100, v32
	v_mov_b32_e32 v101, v32
	v_mov_b32_e32 v102, v32
	v_mov_b32_e32 v103, v32
	v_mov_b32_e32 v112, v32
	v_mov_b32_e32 v113, v32
	v_mov_b32_e32 v114, v32
	v_mov_b32_e32 v115, v32
	v_mov_b32_e32 v116, v32
	v_mov_b32_e32 v117, v32
	v_mov_b32_e32 v118, v32
	v_mov_b32_e32 v119, v32
	v_mov_b32_e32 v128, v32
	v_mov_b32_e32 v129, v32
	v_mov_b32_e32 v130, v32
	v_mov_b32_e32 v131, v32
	v_mov_b32_e32 v132, v32
	v_mov_b32_e32 v133, v32
	v_mov_b32_e32 v134, v32
	v_mov_b32_e32 v135, v32
	v_mov_b32_e32 v144, v32
	v_mov_b32_e32 v145, v32
	v_mov_b32_e32 v146, v32
	v_mov_b32_e32 v147, v32
	v_mov_b32_e32 v148, v32
	v_mov_b32_e32 v149, v32
	v_mov_b32_e32 v150, v32
	v_mov_b32_e32 v151, v32
	v_mov_b32_e32 v104, v32
	v_mov_b32_e32 v105, v32
	v_mov_b32_e32 v106, v32
	v_mov_b32_e32 v107, v32
	v_mov_b32_e32 v108, v32
	v_mov_b32_e32 v109, v32
	v_mov_b32_e32 v110, v32
	v_mov_b32_e32 v111, v32
	v_mov_b32_e32 v120, v32
	v_mov_b32_e32 v121, v32
	v_mov_b32_e32 v122, v32
	v_mov_b32_e32 v123, v32
	v_mov_b32_e32 v124, v32
	v_mov_b32_e32 v125, v32
	v_mov_b32_e32 v126, v32
	v_mov_b32_e32 v127, v32
	v_mov_b32_e32 v136, v32
	v_mov_b32_e32 v137, v32
	v_mov_b32_e32 v138, v32
	v_mov_b32_e32 v139, v32
	v_mov_b32_e32 v140, v32
	v_mov_b32_e32 v141, v32
	v_mov_b32_e32 v142, v32
	v_mov_b32_e32 v143, v32
	v_mov_b32_e32 v152, v32
	v_mov_b32_e32 v153, v32
	v_mov_b32_e32 v154, v32
	v_mov_b32_e32 v155, v32
	v_mov_b32_e32 v156, v32
	v_mov_b32_e32 v157, v32
	v_mov_b32_e32 v158, v32
	v_mov_b32_e32 v159, v32
	v_mov_b32_e32 v92, v32
	v_mov_b32_e32 v93, v32
	v_mov_b32_e32 v94, v32
	v_mov_b32_e32 v95, v32
	v_mov_b32_e32 v88, v32
	v_mov_b32_e32 v89, v32
	v_mov_b32_e32 v90, v32
	v_mov_b32_e32 v91, v32
	v_mov_b32_e32 v76, v32
	v_mov_b32_e32 v77, v32
	v_mov_b32_e32 v78, v32
	v_mov_b32_e32 v79, v32
	v_mov_b32_e32 v72, v32
	v_mov_b32_e32 v73, v32
	v_mov_b32_e32 v74, v32
	v_mov_b32_e32 v75, v32
	v_mov_b32_e32 v60, v32
	v_mov_b32_e32 v61, v32
	v_mov_b32_e32 v62, v32
	v_mov_b32_e32 v63, v32
	v_mov_b32_e32 v56, v32
	v_mov_b32_e32 v57, v32
	v_mov_b32_e32 v58, v32
	v_mov_b32_e32 v59, v32
	v_mov_b32_e32 v44, v32
	v_mov_b32_e32 v45, v32
	v_mov_b32_e32 v46, v32
	v_mov_b32_e32 v47, v32
	v_mov_b32_e32 v40, v32
	v_mov_b32_e32 v41, v32
	v_mov_b32_e32 v42, v32
	v_mov_b32_e32 v43, v32
	v_add_u32_e32 v238, 0x18000, v184
	v_add_u32_e32 v239, 0x18000, v185
.LBB0_361:
	ds_read_b128 v[24:27], v186
	ds_read_b128 v[28:31], v187
	ds_read_b128 v[16:19], v188
	ds_read_b128 v[20:23], v189
	ds_read_b128 v[8:11], v190
	ds_read_b128 v[12:15], v191
	ds_read_b128 v[0:3], v192
	ds_read_b128 v[4:7], v193
	s_add_u32 s41, s56, 0xfff80080
	s_addc_u32 s48, s57, -1
	s_cmp_eq_u32 s40, 28
	s_cselect_b32 s83, s43, s48
	s_cselect_b32 s82, s42, s41
	s_cselect_b32 s59, s37, s39
	s_cselect_b32 s58, s36, s38
	s_add_i32 m0, s12, 0xc000
	ds_read_b128 v[174:177], v194
	ds_read_b128 v[204:207], v194 offset:2048
	ds_read_b128 v[178:181], v195
	ds_read_b128 v[208:211], v195 offset:2048
	ds_read_b128 v[212:215], v194 offset:4096
	ds_read_b128 v[220:223], v194 offset:6144
	ds_read_b128 v[216:219], v195 offset:4096
	ds_read_b128 v[224:227], v195 offset:6144
	global_load_lds_dwordx4 v160, s[56:57]
	s_add_i32 m0, s12, 0xe000
	s_nop 0
	global_load_lds_dwordx4 v164, s[56:57]
	s_waitcnt vmcnt(8)
	s_waitcnt lgkmcnt(0)
	s_waitcnt lgkmcnt(0)
	v_mfma_scale_f32_16x16x128_f8f6f4 v[156:159], v[24:31], v[174:181], v[156:159], v196, v196 op_sel_hi:[0,0,0]
	v_mfma_scale_f32_16x16x128_f8f6f4 v[152:155], v[16:23], v[174:181], v[152:155], v196, v196 op_sel_hi:[0,0,0]
	s_barrier
	s_setprio 3
	v_mfma_scale_f32_16x16x128_f8f6f4 v[136:139], v[16:23], v[204:211], v[136:139], v196, v196 op_sel_hi:[0,0,0]
	v_mfma_scale_f32_16x16x128_f8f6f4 v[140:143], v[24:31], v[204:211], v[140:143], v196, v196 op_sel_hi:[0,0,0]
	v_mfma_scale_f32_16x16x128_f8f6f4 v[124:127], v[24:31], v[212:219], v[124:127], v196, v196 op_sel_hi:[0,0,0]
	v_mfma_scale_f32_16x16x128_f8f6f4 v[120:123], v[16:23], v[212:219], v[120:123], v196, v196 op_sel_hi:[0,0,0]
	v_mfma_scale_f32_16x16x128_f8f6f4 v[104:107], v[16:23], v[220:227], v[104:107], v196, v196 op_sel_hi:[0,0,0]
	v_mfma_scale_f32_16x16x128_f8f6f4 v[108:111], v[24:31], v[220:227], v[108:111], v196, v196 op_sel_hi:[0,0,0]
	s_setprio 0
	s_setprio 3
	v_mfma_scale_f32_16x16x128_f8f6f4 v[148:151], v[8:15], v[174:181], v[148:151], v196, v196 op_sel_hi:[0,0,0]
	v_mfma_scale_f32_16x16x128_f8f6f4 v[144:147], v[0:7], v[174:181], v[144:147], v196, v196 op_sel_hi:[0,0,0]
	v_mfma_scale_f32_16x16x128_f8f6f4 v[128:131], v[0:7], v[204:211], v[128:131], v196, v196 op_sel_hi:[0,0,0]
	v_mfma_scale_f32_16x16x128_f8f6f4 v[132:135], v[8:15], v[204:211], v[132:135], v196, v196 op_sel_hi:[0,0,0]
	v_mfma_scale_f32_16x16x128_f8f6f4 v[116:119], v[8:15], v[212:219], v[116:119], v196, v196 op_sel_hi:[0,0,0]
	v_mfma_scale_f32_16x16x128_f8f6f4 v[112:115], v[0:7], v[212:219], v[112:115], v196, v196 op_sel_hi:[0,0,0]
	v_mfma_scale_f32_16x16x128_f8f6f4 v[96:99], v[0:7], v[220:227], v[96:99], v196, v196 op_sel_hi:[0,0,0]
	v_mfma_scale_f32_16x16x128_f8f6f4 v[100:103], v[8:15], v[220:227], v[100:103], v196, v196 op_sel_hi:[0,0,0]
	s_setprio 0
	s_barrier
; #define PG8_STAGE(bufoff, gbase, voff) do { _Pragma("unroll") for (int _i = 0; _i < 2; ++_i) \
;         __builtin_amdgcn_global_load_lds((const unsigned*)((const char*)(gbase) + (voff)[_i]), (LAS unsigned*)(lds + (bufoff) + ldsw + _i * 8192), 16, 0, 0); } while (0)
; #define PG8_LDA(dst, b, h) do { _Pragma("unroll") for (int m = 0; m < 4; ++m) _Pragma("unroll") for (int k = 0; k < 2; ++k) dst[m][k] = *(const LAS bf16x8*)(lds + PG8_SA(b, h) + aoffk[k] + m * 2048); } while (0)
; #define PG8_LDB(dst, b, h) do { _Pragma("unroll") for (int n = 0; n < 2; ++n) _Pragma("unroll") for (int k = 0; k < 2; ++k) dst[n][k] = *(const LAS bf16x8*)(lds + PG8_SB(b, h) + boffk[k] + n * 2048); } while (0)
; #define PG8_WAIT_V(n) asm volatile("s_waitcnt vmcnt(" #n ")" ::: "memory")
; #define PG8_WAIT_L(n) asm volatile("s_waitcnt lgkmcnt(" #n ")" ::: "memory")
; #define PG8_BAR __builtin_amdgcn_s_barrier()
; #define PG8_SCHED __builtin_amdgcn_sched_barrier(0)
; template <class Epi, class Sched, class GemmT>
; __device__ __forceinline__ void gemm_phase(LAS unsigned char* lds, const GemmT& g, const Sched& S, const Epi& E, const int wid) {
;     ...
;                 PG8_WAIT_V(8); PG8_WAIT_L(0); PG8_BAR; PG8_MMA(0, 0, At, B0); PG8_MMA(0, 1, At, B1); PG8_BAR; PG8_SCHED;
;                 PG8_LDA(At, 0, 1); PG8_STAGE(PG8_SB(0, 0), b2, vB2); PG8_STAGE(PG8_SB(0, 1), b2 + hB2, vB2); PG8_STAGE(PG8_SA(0, 0), a2, vA2);
;                 PG8_WAIT_V(8); PG8_WAIT_L(0); PG8_BAR; PG8_MMA(1, 0, At, B0); PG8_MMA(1, 1, At, B1); PG8_BAR; PG8_SCHED;
;                 PG8_LDB(B0, 1, 0); PG8_LDB(B1, 1, 1); PG8_SCHED; PG8_LDA(At, 1, 0); PG8_STAGE(PG8_SA(0, 1), a2 + hA2, vA2);
	s_add_i32 s41, s64, s68
	s_mov_b32 m0, s41
	ds_read_b128 v[204:207], v194 offset:16384
	ds_read_b128 v[212:215], v194 offset:18432
	ds_read_b128 v[208:211], v195 offset:16384
	ds_read_b128 v[216:219], v195 offset:18432
	ds_read_b128 v[220:223], v194 offset:20480
	ds_read_b128 v[230:233], v194 offset:22528
	ds_read_b128 v[224:227], v195 offset:20480
	ds_read_b128 v[234:237], v195 offset:22528
	global_load_lds_dwordx4 v162, s[58:59]
	s_add_i32 m0, s41, 0x2000
	s_add_u32 s50, s58, 0x80000
	s_addc_u32 s51, s59, 0
	s_add_i32 s41, s65, s68
	global_load_lds_dwordx4 v166, s[58:59]
	s_mov_b32 m0, s41
	s_nop 0
	global_load_lds_dwordx4 v162, s[50:51]
	s_add_i32 m0, s41, 0x2000
	s_nop 0
	global_load_lds_dwordx4 v166, s[50:51]
	s_mov_b32 m0, s12
	s_nop 0
	global_load_lds_dwordx4 v160, s[82:83]
	s_mov_b32 m0, s13
	s_nop 0
	global_load_lds_dwordx4 v164, s[82:83]
	s_waitcnt vmcnt(8)
	s_waitcnt lgkmcnt(0)
	s_waitcnt lgkmcnt(0)
	v_mfma_scale_f32_16x16x128_f8f6f4 v[84:87], v[24:31], v[204:211], v[84:87], v196, v196 op_sel_hi:[0,0,0]
	v_mfma_scale_f32_16x16x128_f8f6f4 v[80:83], v[16:23], v[204:211], v[80:83], v196, v196 op_sel_hi:[0,0,0]
	s_barrier
	s_setprio 3
	v_mfma_scale_f32_16x16x128_f8f6f4 v[64:67], v[16:23], v[212:219], v[64:67], v196, v196 op_sel_hi:[0,0,0]
	v_mfma_scale_f32_16x16x128_f8f6f4 v[68:71], v[24:31], v[212:219], v[68:71], v196, v196 op_sel_hi:[0,0,0]
	v_mfma_scale_f32_16x16x128_f8f6f4 v[52:55], v[24:31], v[220:227], v[52:55], v196, v196 op_sel_hi:[0,0,0]
	v_mfma_scale_f32_16x16x128_f8f6f4 v[48:51], v[16:23], v[220:227], v[48:51], v196, v196 op_sel_hi:[0,0,0]
	v_mfma_scale_f32_16x16x128_f8f6f4 v[32:35], v[16:23], v[230:237], v[32:35], v196, v196 op_sel_hi:[0,0,0]
	v_mfma_scale_f32_16x16x128_f8f6f4 v[36:39], v[24:31], v[230:237], v[36:39], v196, v196 op_sel_hi:[0,0,0]
	s_setprio 0
	s_setprio 3
	v_mfma_scale_f32_16x16x128_f8f6f4 v[92:95], v[8:15], v[204:211], v[92:95], v196, v196 op_sel_hi:[0,0,0]
	v_mfma_scale_f32_16x16x128_f8f6f4 v[88:91], v[0:7], v[204:211], v[88:91], v196, v196 op_sel_hi:[0,0,0]
	v_mfma_scale_f32_16x16x128_f8f6f4 v[72:75], v[0:7], v[212:219], v[72:75], v196, v196 op_sel_hi:[0,0,0]
	v_mfma_scale_f32_16x16x128_f8f6f4 v[76:79], v[8:15], v[212:219], v[76:79], v196, v196 op_sel_hi:[0,0,0]
	v_mfma_scale_f32_16x16x128_f8f6f4 v[60:63], v[8:15], v[220:227], v[60:63], v196, v196 op_sel_hi:[0,0,0]
	v_mfma_scale_f32_16x16x128_f8f6f4 v[56:59], v[0:7], v[220:227], v[56:59], v196, v196 op_sel_hi:[0,0,0]
	v_mfma_scale_f32_16x16x128_f8f6f4 v[40:43], v[0:7], v[230:237], v[40:43], v196, v196 op_sel_hi:[0,0,0]
	v_mfma_scale_f32_16x16x128_f8f6f4 v[44:47], v[8:15], v[230:237], v[44:47], v196, v196 op_sel_hi:[0,0,0]
	s_setprio 0
	s_barrier
	s_add_i32 s41, 0, 0x18000
	s_add_i32 s48, 0, 0x1c000
	v_add_u32_e32 v16, s48, v184
	v_add_u32_e32 v20, s48, v185
	ds_read_b128 v[0:3], v238
	ds_read_b128 v[4:7], v239
	ds_read_b128 v[8:11], v197
	ds_read_b128 v[12:15], v198
	ds_read_b128 v[16:19], v16
	ds_read_b128 v[20:23], v20
	ds_read_b128 v[24:27], v199
	ds_read_b128 v[28:31], v200
	s_add_u32 s50, s82, 0x80000
	s_addc_u32 s51, s83, 0
	s_mov_b32 m0, s15
	ds_read_b128 v[204:207], v194 offset:32768
	ds_read_b128 v[212:215], v194 offset:34816
	ds_read_b128 v[208:211], v195 offset:32768
	ds_read_b128 v[216:219], v195 offset:34816
	ds_read_b128 v[220:223], v194 offset:36864
	ds_read_b128 v[230:233], v194 offset:38912
	ds_read_b128 v[224:227], v195 offset:36864
	ds_read_b128 v[234:237], v195 offset:38912
	global_load_lds_dwordx4 v160, s[50:51]
	s_mov_b32 m0, s21
	s_nop 0
	global_load_lds_dwordx4 v164, s[50:51]
	s_waitcnt vmcnt(8)
	s_waitcnt lgkmcnt(0)
	s_waitcnt lgkmcnt(0)
	v_mfma_scale_f32_16x16x128_f8f6f4 v[156:159], v[0:7], v[204:211], v[156:159], v196, v196 op_sel_hi:[0,0,0]
	v_mfma_scale_f32_16x16x128_f8f6f4 v[152:155], v[8:15], v[204:211], v[152:155], v196, v196 op_sel_hi:[0,0,0]
	s_barrier
; #define PG8_STAGE(bufoff, gbase, voff) do { _Pragma("unroll") for (int _i = 0; _i < 2; ++_i) \
;         __builtin_amdgcn_global_load_lds((const unsigned*)((const char*)(gbase) + (voff)[_i]), (LAS unsigned*)(lds + (bufoff) + ldsw + _i * 8192), 16, 0, 0); } while (0)
; #define PG8_LDA(dst, b, h) do { _Pragma("unroll") for (int m = 0; m < 4; ++m) _Pragma("unroll") for (int k = 0; k < 2; ++k) dst[m][k] = *(const LAS bf16x8*)(lds + PG8_SA(b, h) + aoffk[k] + m * 2048); } while (0)
; #define PG8_LDB(dst, b, h) do { _Pragma("unroll") for (int n = 0; n < 2; ++n) _Pragma("unroll") for (int k = 0; k < 2; ++k) dst[n][k] = *(const LAS bf16x8*)(lds + PG8_SB(b, h) + boffk[k] + n * 2048); } while (0)
; #define PG8_WAIT_V(n) asm volatile("s_waitcnt vmcnt(" #n ")" ::: "memory")
; #define PG8_WAIT_L(n) asm volatile("s_waitcnt lgkmcnt(" #n ")" ::: "memory")
; #define PG8_BAR __builtin_amdgcn_s_barrier()
; #define PG8_SCHED __builtin_amdgcn_sched_barrier(0)
; template <class Epi, class Sched, class GemmT>
; __device__ __forceinline__ void gemm_phase(LAS unsigned char* lds, const GemmT& g, const Sched& S, const Epi& E, const int wid) {
;     ...
;                 PG8_LDB(B0, 1, 0); PG8_LDB(B1, 1, 1); PG8_SCHED; PG8_LDA(At, 1, 0); PG8_STAGE(PG8_SA(0, 1), a2 + hA2, vA2);
;                 PG8_WAIT_V(8); PG8_WAIT_L(0); PG8_BAR; PG8_MMA(0, 0, At, B0); PG8_MMA(0, 1, At, B1); PG8_BAR; PG8_SCHED;
;                 PG8_LDA(At, 1, 1); PG8_STAGE(PG8_SB(1, 0), b3, vB2); PG8_STAGE(PG8_SB(1, 1), b3 + hB2, vB2); PG8_STAGE(PG8_SA(1, 0), a3, vA2);
;                 PG8_WAIT_V(8); PG8_WAIT_L(0); PG8_BAR; PG8_MMA(1, 0, At, B0); PG8_MMA(1, 1, At, B1); PG8_BAR; PG8_SCHED;
;             }
	s_setprio 3
	v_mfma_scale_f32_16x16x128_f8f6f4 v[136:139], v[8:15], v[212:219], v[136:139], v196, v196 op_sel_hi:[0,0,0]
	v_mfma_scale_f32_16x16x128_f8f6f4 v[140:143], v[0:7], v[212:219], v[140:143], v196, v196 op_sel_hi:[0,0,0]
	v_mfma_scale_f32_16x16x128_f8f6f4 v[124:127], v[0:7], v[220:227], v[124:127], v196, v196 op_sel_hi:[0,0,0]
	v_mfma_scale_f32_16x16x128_f8f6f4 v[120:123], v[8:15], v[220:227], v[120:123], v196, v196 op_sel_hi:[0,0,0]
	v_mfma_scale_f32_16x16x128_f8f6f4 v[104:107], v[8:15], v[230:237], v[104:107], v196, v196 op_sel_hi:[0,0,0]
	v_mfma_scale_f32_16x16x128_f8f6f4 v[108:111], v[0:7], v[230:237], v[108:111], v196, v196 op_sel_hi:[0,0,0]
	s_setprio 0
	s_setprio 3
	v_mfma_scale_f32_16x16x128_f8f6f4 v[148:151], v[16:23], v[204:211], v[148:151], v196, v196 op_sel_hi:[0,0,0]
	v_mfma_scale_f32_16x16x128_f8f6f4 v[144:147], v[24:31], v[204:211], v[144:147], v196, v196 op_sel_hi:[0,0,0]
	v_mfma_scale_f32_16x16x128_f8f6f4 v[128:131], v[24:31], v[212:219], v[128:131], v196, v196 op_sel_hi:[0,0,0]
	v_mfma_scale_f32_16x16x128_f8f6f4 v[132:135], v[16:23], v[212:219], v[132:135], v196, v196 op_sel_hi:[0,0,0]
	v_mfma_scale_f32_16x16x128_f8f6f4 v[116:119], v[16:23], v[220:227], v[116:119], v196, v196 op_sel_hi:[0,0,0]
	v_mfma_scale_f32_16x16x128_f8f6f4 v[112:115], v[24:31], v[220:227], v[112:115], v196, v196 op_sel_hi:[0,0,0]
	v_mfma_scale_f32_16x16x128_f8f6f4 v[96:99], v[24:31], v[230:237], v[96:99], v196, v196 op_sel_hi:[0,0,0]
	v_mfma_scale_f32_16x16x128_f8f6f4 v[100:103], v[16:23], v[230:237], v[100:103], v196, v196 op_sel_hi:[0,0,0]
	s_setprio 0
	s_barrier
	s_add_i32 s41, s41, s68
	s_mov_b32 m0, s41
	ds_read_b128 v[204:207], v194 offset:49152
	ds_read_b128 v[212:215], v194 offset:51200
	ds_read_b128 v[208:211], v195 offset:49152
	ds_read_b128 v[216:219], v195 offset:51200
	ds_read_b128 v[220:223], v194 offset:53248
	ds_read_b128 v[230:233], v194 offset:55296
	ds_read_b128 v[224:227], v195 offset:53248
	ds_read_b128 v[234:237], v195 offset:55296
	s_add_u32 s98, s58, 0x80
	s_addc_u32 s99, s59, 0
	s_nop 0
	global_load_lds_dwordx4 v162, s[98:99]
	s_add_i32 m0, s41, 0x2000
	s_add_u32 s50, s58, 0x80080
	s_addc_u32 s51, s59, 0
	s_add_i32 s41, s48, s68
	global_load_lds_dwordx4 v166, s[98:99]
	s_mov_b32 m0, s41
	s_nop 0
	global_load_lds_dwordx4 v162, s[50:51]
	s_add_i32 m0, s41, 0x2000
	s_nop 0
	global_load_lds_dwordx4 v166, s[50:51]
	s_mov_b32 m0, s35
	s_nop 0
	s_add_u32 s98, s82, 0x80
	s_addc_u32 s99, s83, 0
	s_nop 0
	global_load_lds_dwordx4 v160, s[98:99]
	s_mov_b32 m0, s53
	s_nop 0
	global_load_lds_dwordx4 v164, s[98:99]
	s_waitcnt vmcnt(8)
	s_waitcnt lgkmcnt(0)
	s_waitcnt lgkmcnt(0)
	v_mfma_scale_f32_16x16x128_f8f6f4 v[84:87], v[0:7], v[204:211], v[84:87], v196, v196 op_sel_hi:[0,0,0]
	v_mfma_scale_f32_16x16x128_f8f6f4 v[80:83], v[8:15], v[204:211], v[80:83], v196, v196 op_sel_hi:[0,0,0]
	s_barrier
	s_setprio 3
	v_mfma_scale_f32_16x16x128_f8f6f4 v[64:67], v[8:15], v[212:219], v[64:67], v196, v196 op_sel_hi:[0,0,0]
	v_mfma_scale_f32_16x16x128_f8f6f4 v[68:71], v[0:7], v[212:219], v[68:71], v196, v196 op_sel_hi:[0,0,0]
	v_mfma_scale_f32_16x16x128_f8f6f4 v[52:55], v[0:7], v[220:227], v[52:55], v196, v196 op_sel_hi:[0,0,0]
	v_mfma_scale_f32_16x16x128_f8f6f4 v[48:51], v[8:15], v[220:227], v[48:51], v196, v196 op_sel_hi:[0,0,0]
	v_mfma_scale_f32_16x16x128_f8f6f4 v[32:35], v[8:15], v[230:237], v[32:35], v196, v196 op_sel_hi:[0,0,0]
	v_mfma_scale_f32_16x16x128_f8f6f4 v[36:39], v[0:7], v[230:237], v[36:39], v196, v196 op_sel_hi:[0,0,0]
	s_setprio 0
	s_setprio 3
	v_mfma_scale_f32_16x16x128_f8f6f4 v[92:95], v[16:23], v[204:211], v[92:95], v196, v196 op_sel_hi:[0,0,0]
	v_mfma_scale_f32_16x16x128_f8f6f4 v[88:91], v[24:31], v[204:211], v[88:91], v196, v196 op_sel_hi:[0,0,0]
	v_mfma_scale_f32_16x16x128_f8f6f4 v[72:75], v[24:31], v[212:219], v[72:75], v196, v196 op_sel_hi:[0,0,0]
	v_mfma_scale_f32_16x16x128_f8f6f4 v[76:79], v[16:23], v[212:219], v[76:79], v196, v196 op_sel_hi:[0,0,0]
	v_mfma_scale_f32_16x16x128_f8f6f4 v[60:63], v[16:23], v[220:227], v[60:63], v196, v196 op_sel_hi:[0,0,0]
	v_mfma_scale_f32_16x16x128_f8f6f4 v[56:59], v[24:31], v[220:227], v[56:59], v196, v196 op_sel_hi:[0,0,0]
	v_mfma_scale_f32_16x16x128_f8f6f4 v[40:43], v[24:31], v[230:237], v[40:43], v196, v196 op_sel_hi:[0,0,0]
	v_mfma_scale_f32_16x16x128_f8f6f4 v[44:47], v[16:23], v[230:237], v[44:47], v196, v196 op_sel_hi:[0,0,0]
	s_setprio 0
	s_barrier
	s_add_i32 s40, s40, 2
	s_add_u32 s56, s56, 0x100
	s_addc_u32 s57, s57, 0
	s_add_u32 s38, s38, 0x100
	s_addc_u32 s39, s39, 0
	s_cmp_gt_u32 s40, 29
	s_cbranch_scc0 .LBB0_361
	s_and_b64 vcc, exec, s[16:17]
	s_cbranch_vccz .LBB0_364
	s_barrier

; #define PG8_BAR __builtin_amdgcn_s_barrier()
; template <class Epi, class Sched, class GemmT>
; __device__ __forceinline__ void gemm_phase(LAS unsigned char* lds, const GemmT& g, const Sched& S, const Epi& E, const int wid) {
;     ...
;     Acc acc;
; #pragma unroll
;     for (int a = 0; a < 2; ++a)
; #pragma unroll
;         for (int b = 0; b < 2; ++b)
; #pragma unroll
;             for (int m = 0; m < 4; ++m)
; #pragma unroll
;                 for (int n = 0; n < 2; ++n) acc[a][b][m][n] = (f32x4){0.f, 0.f, 0.f, 0.f};
;     bf16x8 At[4][2], B0[2][2], B1[2][2];
;     const int sc8 = 0x7f7f7f7f; (void)sc8;
;     Seg cs = g.seg(cur, 0);
;     unsigned voffA[2], voffB[2]; size_t hstepA, hstepB;
;     PG8_VOFFS(voffA, voffB, hstepA, hstepB, cs);
;     const char* cA = cs.A; const char* cB = cs.B;
;     PG8_STAGE(PG8_SB(0, 0), cB, voffB); PG8_STAGE(PG8_SB(0, 1), cB + hstepB, voffB); PG8_STAGE(PG8_SA(0, 0), cA, voffA); PG8_STAGE(PG8_SA(0, 1), cA + hstepA, voffA);
;     if (wr == 1) PG8_BAR;
;     PG8_WAIT_V(2); PG8_BAR;
;     PG8_STAGE(PG8_SB(1, 0), cB + kstep, voffB); PG8_STAGE(PG8_SA(1, 0), cA + kstep, voffA); PG8_STAGE(PG8_SB(1, 1), cB + hstepB + kstep, voffB);
;     PG8_WAIT_V(6); PG8_BAR;
;     for (;;) {
;         const bool has_next = S.next(ui + 1, nxt);
; #pragma unroll 1
;         for (int sgi = 0; sgi < NSEG; ++sgi) {
;             const Seg ns = (sgi + 1 < NSEG) ? g.seg(cur, sgi + 1) : g.seg(has_next ? nxt : cur, 0);
;             unsigned nvA[2], nvB[2]; size_t nhA, nhB;
;             if constexpr (GemmT::UNIFORM) { nvA[0] = voffA[0]; nvA[1] = voffA[1]; nvB[0] = voffB[0]; nvB[1] = voffB[1]; nhA = hstepA; nhB = hstepB; }
;             else PG8_VOFFS(nvA, nvB, nhA, nhB, ns);
;             const int nt = cs.nt;
;             for (int t = 0; t < nt; t += 2) {
;                 const bool last = (t == nt - 2);
;                 const char* a1 = cA + (size_t)(t + 1) * kstep;
;                 const char* a2 = last ? ns.A : cA + (size_t)(t + 2) * kstep; const char* b2 = last ? ns.B : cB + (size_t)(t + 2) * kstep;
;                 const char* a3 = a2 + kstep; const char* b3 = b2 + kstep;
;                 unsigned vA2[2], vB2[2];
; #pragma unroll
;                 for (int i = 0; i < 2; ++i) { vA2[i] = last ? nvA[i] : voffA[i]; vB2[i] = last ? nvB[i] : voffB[i]; }
;                 const size_t hA2 = last ? nhA : hstepA, hB2 = last ? nhB : hstepB;
.LBB0_416:
	s_ashr_i32 s71, s70, 31
	v_readlane_b32 s72, v254, 4
	s_ashr_i32 s59, s58, 31
	s_lshl_b64 s[36:37], s[70:71], 21
	v_readlane_b32 s76, v254, 8
	v_readlane_b32 s77, v254, 9
	s_add_u32 s56, s76, s36
	s_addc_u32 s57, s77, s37
	s_lshl_b64 s[58:59], s[58:59], 21
	v_readlane_b32 s26, v255, 7
	v_readlane_b32 s27, v255, 8
	s_add_u32 s5, s26, s58
	s_addc_u32 s16, s27, s59
	s_add_u32 s84, s84, 0x100080
	s_addc_u32 s85, s85, 0
	s_add_u32 s36, s19, s86
	v_mov_b32_e32 v0, 0
	s_addc_u32 s37, s34, s87
	s_mov_b32 s38, -2
	v_mov_b32_e32 v1, v0
	v_mov_b32_e32 v2, v0
	v_mov_b32_e32 v3, v0
	v_mov_b32_e32 v4, v0
	v_mov_b32_e32 v5, v0
	v_mov_b32_e32 v6, v0
	v_mov_b32_e32 v7, v0
	v_mov_b32_e32 v8, v0
	v_mov_b32_e32 v9, v0
	v_mov_b32_e32 v10, v0
	v_mov_b32_e32 v11, v0
	v_mov_b32_e32 v12, v0
	v_mov_b32_e32 v13, v0
	v_mov_b32_e32 v14, v0
	v_mov_b32_e32 v15, v0
	v_mov_b32_e32 v16, v0
	v_mov_b32_e32 v17, v0
	v_mov_b32_e32 v18, v0
	v_mov_b32_e32 v19, v0
	v_mov_b32_e32 v20, v0
	v_mov_b32_e32 v21, v0
	v_mov_b32_e32 v22, v0
	v_mov_b32_e32 v23, v0
	v_mov_b32_e32 v24, v0
	v_mov_b32_e32 v25, v0
	v_mov_b32_e32 v26, v0
	v_mov_b32_e32 v27, v0
	v_mov_b32_e32 v28, v0
	v_mov_b32_e32 v29, v0
	v_mov_b32_e32 v30, v0
	v_mov_b32_e32 v31, v0
	v_mov_b32_e32 v40, v0
	v_mov_b32_e32 v41, v0
	v_mov_b32_e32 v42, v0
	v_mov_b32_e32 v43, v0
	v_mov_b32_e32 v48, v0
	v_mov_b32_e32 v49, v0
	v_mov_b32_e32 v50, v0
	v_mov_b32_e32 v51, v0
	v_mov_b32_e32 v64, v0
	v_mov_b32_e32 v65, v0
	v_mov_b32_e32 v66, v0
	v_mov_b32_e32 v67, v0
	v_mov_b32_e32 v68, v0
	v_mov_b32_e32 v69, v0
	v_mov_b32_e32 v70, v0
	v_mov_b32_e32 v71, v0
	v_mov_b32_e32 v88, v0
	v_mov_b32_e32 v89, v0
	v_mov_b32_e32 v90, v0
	v_mov_b32_e32 v91, v0
	v_mov_b32_e32 v92, v0
	v_mov_b32_e32 v93, v0
	v_mov_b32_e32 v94, v0
	v_mov_b32_e32 v95, v0
	v_mov_b32_e32 v104, v0
	v_mov_b32_e32 v105, v0
	v_mov_b32_e32 v106, v0
	v_mov_b32_e32 v107, v0
	v_mov_b32_e32 v108, v0
	v_mov_b32_e32 v109, v0
	v_mov_b32_e32 v110, v0
	v_mov_b32_e32 v111, v0
	v_mov_b32_e32 v76, v0
	v_mov_b32_e32 v77, v0
	v_mov_b32_e32 v78, v0
	v_mov_b32_e32 v79, v0
	v_mov_b32_e32 v84, v0
	v_mov_b32_e32 v85, v0
	v_mov_b32_e32 v86, v0
	v_mov_b32_e32 v87, v0
	v_mov_b32_e32 v96, v0
	v_mov_b32_e32 v97, v0
	v_mov_b32_e32 v98, v0
	v_mov_b32_e32 v99, v0
	v_mov_b32_e32 v100, v0
	v_mov_b32_e32 v101, v0
	v_mov_b32_e32 v102, v0
	v_mov_b32_e32 v103, v0
	v_mov_b32_e32 v112, v0
	v_mov_b32_e32 v113, v0
	v_mov_b32_e32 v114, v0
	v_mov_b32_e32 v115, v0
	v_mov_b32_e32 v116, v0
	v_mov_b32_e32 v117, v0
	v_mov_b32_e32 v118, v0
	v_mov_b32_e32 v119, v0
	v_mov_b32_e32 v120, v0
	v_mov_b32_e32 v121, v0
	v_mov_b32_e32 v122, v0
	v_mov_b32_e32 v123, v0
	v_mov_b32_e32 v124, v0
	v_mov_b32_e32 v125, v0
	v_mov_b32_e32 v126, v0
	v_mov_b32_e32 v127, v0
	v_mov_b32_e32 v80, v0
	v_mov_b32_e32 v81, v0
	v_mov_b32_e32 v82, v0
	v_mov_b32_e32 v83, v0
	v_mov_b32_e32 v72, v0
	v_mov_b32_e32 v73, v0
	v_mov_b32_e32 v74, v0
	v_mov_b32_e32 v75, v0
	v_mov_b32_e32 v60, v0
	v_mov_b32_e32 v61, v0
	v_mov_b32_e32 v62, v0
	v_mov_b32_e32 v63, v0
	v_mov_b32_e32 v56, v0
	v_mov_b32_e32 v57, v0
	v_mov_b32_e32 v58, v0
	v_mov_b32_e32 v59, v0
	v_mov_b32_e32 v52, v0
	v_mov_b32_e32 v53, v0
	v_mov_b32_e32 v54, v0
	v_mov_b32_e32 v55, v0
	v_mov_b32_e32 v44, v0
	v_mov_b32_e32 v45, v0
	v_mov_b32_e32 v46, v0
	v_mov_b32_e32 v47, v0
	v_mov_b32_e32 v36, v0
	v_mov_b32_e32 v37, v0
	v_mov_b32_e32 v38, v0
	v_mov_b32_e32 v39, v0
	v_mov_b32_e32 v32, v0
	v_mov_b32_e32 v33, v0
	v_mov_b32_e32 v34, v0
	v_mov_b32_e32 v35, v0
	v_readlane_b32 s73, v254, 5
	v_readlane_b32 s74, v254, 6
	v_readlane_b32 s75, v254, 7
	v_readlane_b32 s78, v254, 10
	v_readlane_b32 s79, v254, 11
	v_add_u32_e32 v176, 0x18000, v187
	v_add_u32_e32 v177, 0x18000, v190
	v_add_u32_e32 v180, 0x1c000, v187
	v_add_u32_e32 v181, 0x1c000, v190
.LBB0_417:
	ds_read_b128 v[140:143], v192
	ds_read_b128 v[144:147], v193
	ds_read_b128 v[148:151], v194
	ds_read_b128 v[152:155], v195
	ds_read_b128 v[156:159], v196
	ds_read_b128 v[160:163], v197
	ds_read_b128 v[164:167], v198
	ds_read_b128 v[168:171], v199
	s_add_u32 s39, s84, 0xfff00080
	s_addc_u32 s40, s85, -1
	s_cmp_eq_u32 s38, 60
	s_cselect_b32 s87, s57, s40
	s_cselect_b32 s86, s56, s39
	s_cselect_b32 s71, s16, s37
	s_cselect_b32 s70, s5, s36
	s_add_i32 m0, s9, 0xc000
	ds_read_b128 v[172:175], v200
	ds_read_b128 v[208:211], v200 offset:2048
	ds_read_b128 v[212:215], v201
	ds_read_b128 v[216:219], v201 offset:2048
	ds_read_b128 v[220:223], v200 offset:4096
	ds_read_b128 v[224:227], v200 offset:6144
	ds_read_b128 v[230:233], v201 offset:4096
	ds_read_b128 v[234:237], v201 offset:6144
	global_load_lds_dwordx4 v128, s[84:85]
	s_add_i32 m0, s9, 0xe000
	s_nop 0
	global_load_lds_dwordx4 v132, s[84:85]
	s_waitcnt vmcnt(8)
	s_waitcnt lgkmcnt(0)
	s_waitcnt lgkmcnt(0)
	v_mfma_f32_16x16x32_bf16 v[124:127], v[140:143], v[172:175], v[124:127]
	v_mfma_f32_16x16x32_bf16 v[124:127], v[144:147], v[212:215], v[124:127]
	v_mfma_f32_16x16x32_bf16 v[120:123], v[152:155], v[212:215], v[120:123]
	v_mfma_f32_16x16x32_bf16 v[120:123], v[148:151], v[172:175], v[120:123]
	s_barrier
; #define PG8_STAGE(bufoff, gbase, voff) do { _Pragma("unroll") for (int _i = 0; _i < 2; ++_i) \
;         __builtin_amdgcn_global_load_lds((const unsigned*)((const char*)(gbase) + (voff)[_i]), (LAS unsigned*)(lds + (bufoff) + ldsw + _i * 8192), 16, 0, 0); } while (0)
; #define PG8_LDA(dst, b, h) do { _Pragma("unroll") for (int m = 0; m < 4; ++m) _Pragma("unroll") for (int k = 0; k < 2; ++k) dst[m][k] = *(const LAS bf16x8*)(lds + PG8_SA(b, h) + aoffk[k] + m * 2048); } while (0)
; #define PG8_WAIT_V(n) asm volatile("s_waitcnt vmcnt(" #n ")" ::: "memory")
; #define PG8_WAIT_L(n) asm volatile("s_waitcnt lgkmcnt(" #n ")" ::: "memory")
; #define PG8_BAR __builtin_amdgcn_s_barrier()
; #define PG8_SCHED __builtin_amdgcn_sched_barrier(0)
; template <class Epi, class Sched, class GemmT>
; __device__ __forceinline__ void gemm_phase(LAS unsigned char* lds, const GemmT& g, const Sched& S, const Epi& E, const int wid) {
;     ...
;                 PG8_WAIT_V(8); PG8_WAIT_L(0); PG8_BAR; PG8_MMA(0, 0, At, B0); PG8_MMA(0, 1, At, B1); PG8_BAR; PG8_SCHED;
;                 PG8_LDA(At, 0, 1); PG8_STAGE(PG8_SB(0, 0), b2, vB2); PG8_STAGE(PG8_SB(0, 1), b2 + hB2, vB2); PG8_STAGE(PG8_SA(0, 0), a2, vA2);
;                 PG8_WAIT_V(8); PG8_WAIT_L(0); PG8_BAR; PG8_MMA(1, 0, At, B0); PG8_MMA(1, 1, At, B1); PG8_BAR; PG8_SCHED;
	s_setprio 3
	v_mfma_f32_16x16x32_bf16 v[112:115], v[148:151], v[208:211], v[112:115]
	v_mfma_f32_16x16x32_bf16 v[112:115], v[152:155], v[216:219], v[112:115]
	v_mfma_f32_16x16x32_bf16 v[116:119], v[144:147], v[216:219], v[116:119]
	v_mfma_f32_16x16x32_bf16 v[116:119], v[140:143], v[208:211], v[116:119]
	v_mfma_f32_16x16x32_bf16 v[100:103], v[140:143], v[220:223], v[100:103]
	v_mfma_f32_16x16x32_bf16 v[100:103], v[144:147], v[230:233], v[100:103]
	v_mfma_f32_16x16x32_bf16 v[96:99], v[152:155], v[230:233], v[96:99]
	v_mfma_f32_16x16x32_bf16 v[96:99], v[148:151], v[220:223], v[96:99]
	v_mfma_f32_16x16x32_bf16 v[76:79], v[148:151], v[224:227], v[76:79]
	v_mfma_f32_16x16x32_bf16 v[76:79], v[152:155], v[234:237], v[76:79]
	v_mfma_f32_16x16x32_bf16 v[84:87], v[144:147], v[234:237], v[84:87]
	v_mfma_f32_16x16x32_bf16 v[84:87], v[140:143], v[224:227], v[84:87]
	s_setprio 0
	s_setprio 3
	v_mfma_f32_16x16x32_bf16 v[108:111], v[156:159], v[172:175], v[108:111]
	v_mfma_f32_16x16x32_bf16 v[108:111], v[160:163], v[212:215], v[108:111]
	v_mfma_f32_16x16x32_bf16 v[104:107], v[168:171], v[212:215], v[104:107]
	v_mfma_f32_16x16x32_bf16 v[104:107], v[164:167], v[172:175], v[104:107]
	v_mfma_f32_16x16x32_bf16 v[88:91], v[164:167], v[208:211], v[88:91]
	v_mfma_f32_16x16x32_bf16 v[88:91], v[168:171], v[216:219], v[88:91]
	v_mfma_f32_16x16x32_bf16 v[92:95], v[160:163], v[216:219], v[92:95]
	v_mfma_f32_16x16x32_bf16 v[92:95], v[156:159], v[208:211], v[92:95]
	v_mfma_f32_16x16x32_bf16 v[68:71], v[156:159], v[220:223], v[68:71]
	v_mfma_f32_16x16x32_bf16 v[68:71], v[160:163], v[230:233], v[68:71]
	v_mfma_f32_16x16x32_bf16 v[64:67], v[168:171], v[230:233], v[64:67]
	v_mfma_f32_16x16x32_bf16 v[64:67], v[164:167], v[220:223], v[64:67]
	v_mfma_f32_16x16x32_bf16 v[40:43], v[164:167], v[224:227], v[40:43]
	v_mfma_f32_16x16x32_bf16 v[40:43], v[168:171], v[234:237], v[40:43]
	v_mfma_f32_16x16x32_bf16 v[48:51], v[160:163], v[234:237], v[48:51]
	v_mfma_f32_16x16x32_bf16 v[48:51], v[156:159], v[224:227], v[48:51]
	s_setprio 0
	s_barrier
	s_add_i32 s39, s35, s68
	s_mov_b32 m0, s39
	ds_read_b128 v[172:175], v200 offset:16384
	ds_read_b128 v[208:211], v200 offset:18432
	ds_read_b128 v[212:215], v201 offset:16384
	ds_read_b128 v[216:219], v201 offset:18432
	ds_read_b128 v[220:223], v200 offset:20480
	ds_read_b128 v[224:227], v200 offset:22528
	ds_read_b128 v[230:233], v201 offset:20480
	ds_read_b128 v[234:237], v201 offset:22528
	global_load_lds_dwordx4 v130, s[70:71]
	s_add_i32 m0, s39, 0x2000
	s_add_u32 s40, s70, 0x100000
	s_addc_u32 s41, s71, 0
	s_add_i32 s39, s69, s68
	global_load_lds_dwordx4 v134, s[70:71]
	s_mov_b32 m0, s39
	s_nop 0
	global_load_lds_dwordx4 v130, s[40:41]
	s_add_i32 m0, s39, 0x2000
	s_nop 0
	global_load_lds_dwordx4 v134, s[40:41]
	s_mov_b32 m0, s9
	s_nop 0
	global_load_lds_dwordx4 v128, s[86:87]
	s_mov_b32 m0, s29
	s_nop 0
	global_load_lds_dwordx4 v132, s[86:87]
	s_waitcnt vmcnt(8)
	s_waitcnt lgkmcnt(0)
	s_waitcnt lgkmcnt(0)
	v_mfma_f32_16x16x32_bf16 v[28:31], v[140:143], v[172:175], v[28:31]
	v_mfma_f32_16x16x32_bf16 v[28:31], v[144:147], v[212:215], v[28:31]
	v_mfma_f32_16x16x32_bf16 v[24:27], v[152:155], v[212:215], v[24:27]
	v_mfma_f32_16x16x32_bf16 v[24:27], v[148:151], v[172:175], v[24:27]
	s_barrier
	s_setprio 3
	v_mfma_f32_16x16x32_bf16 v[16:19], v[148:151], v[208:211], v[16:19]
	v_mfma_f32_16x16x32_bf16 v[16:19], v[152:155], v[216:219], v[16:19]
	v_mfma_f32_16x16x32_bf16 v[20:23], v[144:147], v[216:219], v[20:23]
	v_mfma_f32_16x16x32_bf16 v[20:23], v[140:143], v[208:211], v[20:23]
	v_mfma_f32_16x16x32_bf16 v[12:15], v[140:143], v[220:223], v[12:15]
	v_mfma_f32_16x16x32_bf16 v[12:15], v[144:147], v[230:233], v[12:15]
	v_mfma_f32_16x16x32_bf16 v[8:11], v[152:155], v[230:233], v[8:11]
	v_mfma_f32_16x16x32_bf16 v[8:11], v[148:151], v[220:223], v[8:11]
	v_mfma_f32_16x16x32_bf16 v[0:3], v[148:151], v[224:227], v[0:3]
	v_mfma_f32_16x16x32_bf16 v[0:3], v[152:155], v[234:237], v[0:3]
	v_mfma_f32_16x16x32_bf16 v[4:7], v[144:147], v[234:237], v[4:7]
	v_mfma_f32_16x16x32_bf16 v[4:7], v[140:143], v[224:227], v[4:7]
	s_setprio 0
	s_setprio 3
	v_mfma_f32_16x16x32_bf16 v[80:83], v[156:159], v[172:175], v[80:83]
	v_mfma_f32_16x16x32_bf16 v[80:83], v[160:163], v[212:215], v[80:83]
	v_mfma_f32_16x16x32_bf16 v[72:75], v[168:171], v[212:215], v[72:75]
	v_mfma_f32_16x16x32_bf16 v[72:75], v[164:167], v[172:175], v[72:75]
	v_mfma_f32_16x16x32_bf16 v[56:59], v[164:167], v[208:211], v[56:59]
	v_mfma_f32_16x16x32_bf16 v[56:59], v[168:171], v[216:219], v[56:59]
	v_mfma_f32_16x16x32_bf16 v[60:63], v[160:163], v[216:219], v[60:63]
	v_mfma_f32_16x16x32_bf16 v[60:63], v[156:159], v[208:211], v[60:63]
	v_mfma_f32_16x16x32_bf16 v[52:55], v[156:159], v[220:223], v[52:55]
	v_mfma_f32_16x16x32_bf16 v[52:55], v[160:163], v[230:233], v[52:55]
	v_mfma_f32_16x16x32_bf16 v[44:47], v[168:171], v[230:233], v[44:47]
	v_mfma_f32_16x16x32_bf16 v[44:47], v[164:167], v[220:223], v[44:47]
	v_mfma_f32_16x16x32_bf16 v[32:35], v[164:167], v[224:227], v[32:35]
	v_mfma_f32_16x16x32_bf16 v[32:35], v[168:171], v[234:237], v[32:35]
	v_mfma_f32_16x16x32_bf16 v[36:39], v[160:163], v[234:237], v[36:39]
	v_mfma_f32_16x16x32_bf16 v[36:39], v[156:159], v[224:227], v[36:39]
	s_setprio 0
	s_barrier
; #define PG8_STAGE(bufoff, gbase, voff) do { _Pragma("unroll") for (int _i = 0; _i < 2; ++_i) \
;         __builtin_amdgcn_global_load_lds((const unsigned*)((const char*)(gbase) + (voff)[_i]), (LAS unsigned*)(lds + (bufoff) + ldsw + _i * 8192), 16, 0, 0); } while (0)
; #define PG8_LDA(dst, b, h) do { _Pragma("unroll") for (int m = 0; m < 4; ++m) _Pragma("unroll") for (int k = 0; k < 2; ++k) dst[m][k] = *(const LAS bf16x8*)(lds + PG8_SA(b, h) + aoffk[k] + m * 2048); } while (0)
; #define PG8_LDB(dst, b, h) do { _Pragma("unroll") for (int n = 0; n < 2; ++n) _Pragma("unroll") for (int k = 0; k < 2; ++k) dst[n][k] = *(const LAS bf16x8*)(lds + PG8_SB(b, h) + boffk[k] + n * 2048); } while (0)
; #define PG8_WAIT_V(n) asm volatile("s_waitcnt vmcnt(" #n ")" ::: "memory")
; #define PG8_WAIT_L(n) asm volatile("s_waitcnt lgkmcnt(" #n ")" ::: "memory")
; #define PG8_BAR __builtin_amdgcn_s_barrier()
; #define PG8_SCHED __builtin_amdgcn_sched_barrier(0)
; template <class Epi, class Sched, class GemmT>
; __device__ __forceinline__ void gemm_phase(LAS unsigned char* lds, const GemmT& g, const Sched& S, const Epi& E, const int wid) {
;     ...
;                 PG8_LDB(B0, 1, 0); PG8_LDB(B1, 1, 1); PG8_SCHED; PG8_LDA(At, 1, 0); PG8_STAGE(PG8_SA(0, 1), a2 + hA2, vA2);
;                 PG8_WAIT_V(8); PG8_WAIT_L(0); PG8_BAR; PG8_MMA(0, 0, At, B0); PG8_MMA(0, 1, At, B1); PG8_BAR; PG8_SCHED;
;                 PG8_LDA(At, 1, 1); PG8_STAGE(PG8_SB(1, 0), b3, vB2); PG8_STAGE(PG8_SB(1, 1), b3 + hB2, vB2); PG8_STAGE(PG8_SA(1, 0), a3, vA2);
;                 PG8_WAIT_V(8); PG8_WAIT_L(0); PG8_BAR; PG8_MMA(1, 0, At, B0); PG8_MMA(1, 1, At, B1); PG8_BAR; PG8_SCHED;
;             }
	s_add_i32 s39, 0, 0x18000
	s_add_i32 s48, 0, 0x1c000
	ds_read_b128 v[140:143], v176
	ds_read_b128 v[144:147], v177
	ds_read_b128 v[148:151], v202
	ds_read_b128 v[152:155], v203
	ds_read_b128 v[156:159], v180
	ds_read_b128 v[160:163], v181
	ds_read_b128 v[164:167], v204
	ds_read_b128 v[168:171], v205
	s_add_u32 s40, s86, 0x100000
	s_addc_u32 s41, s87, 0
	s_mov_b32 m0, s93
	ds_read_b128 v[172:175], v200 offset:32768
	ds_read_b128 v[208:211], v200 offset:34816
	ds_read_b128 v[212:215], v201 offset:32768
	ds_read_b128 v[216:219], v201 offset:34816
	ds_read_b128 v[220:223], v200 offset:36864
	ds_read_b128 v[224:227], v200 offset:38912
	ds_read_b128 v[230:233], v201 offset:36864
	ds_read_b128 v[234:237], v201 offset:38912
	global_load_lds_dwordx4 v128, s[40:41]
	s_mov_b32 m0, s6
	s_nop 0
	global_load_lds_dwordx4 v132, s[40:41]
	s_waitcnt vmcnt(8)
	s_waitcnt lgkmcnt(0)
	s_waitcnt lgkmcnt(0)
	v_mfma_f32_16x16x32_bf16 v[124:127], v[140:143], v[172:175], v[124:127]
	v_mfma_f32_16x16x32_bf16 v[124:127], v[144:147], v[212:215], v[124:127]
	v_mfma_f32_16x16x32_bf16 v[120:123], v[152:155], v[212:215], v[120:123]
	v_mfma_f32_16x16x32_bf16 v[120:123], v[148:151], v[172:175], v[120:123]
	s_barrier
	s_setprio 3
	v_mfma_f32_16x16x32_bf16 v[112:115], v[148:151], v[208:211], v[112:115]
	v_mfma_f32_16x16x32_bf16 v[112:115], v[152:155], v[216:219], v[112:115]
	v_mfma_f32_16x16x32_bf16 v[116:119], v[144:147], v[216:219], v[116:119]
	v_mfma_f32_16x16x32_bf16 v[116:119], v[140:143], v[208:211], v[116:119]
	v_mfma_f32_16x16x32_bf16 v[100:103], v[140:143], v[220:223], v[100:103]
	v_mfma_f32_16x16x32_bf16 v[100:103], v[144:147], v[230:233], v[100:103]
	v_mfma_f32_16x16x32_bf16 v[96:99], v[152:155], v[230:233], v[96:99]
	v_mfma_f32_16x16x32_bf16 v[96:99], v[148:151], v[220:223], v[96:99]
	v_mfma_f32_16x16x32_bf16 v[76:79], v[148:151], v[224:227], v[76:79]
	v_mfma_f32_16x16x32_bf16 v[76:79], v[152:155], v[234:237], v[76:79]
	v_mfma_f32_16x16x32_bf16 v[84:87], v[144:147], v[234:237], v[84:87]
	v_mfma_f32_16x16x32_bf16 v[84:87], v[140:143], v[224:227], v[84:87]
	s_setprio 0
	s_setprio 3
	v_mfma_f32_16x16x32_bf16 v[108:111], v[156:159], v[172:175], v[108:111]
	v_mfma_f32_16x16x32_bf16 v[108:111], v[160:163], v[212:215], v[108:111]
	v_mfma_f32_16x16x32_bf16 v[104:107], v[168:171], v[212:215], v[104:107]
	v_mfma_f32_16x16x32_bf16 v[104:107], v[164:167], v[172:175], v[104:107]
	v_mfma_f32_16x16x32_bf16 v[88:91], v[164:167], v[208:211], v[88:91]
	v_mfma_f32_16x16x32_bf16 v[88:91], v[168:171], v[216:219], v[88:91]
	v_mfma_f32_16x16x32_bf16 v[92:95], v[160:163], v[216:219], v[92:95]
	v_mfma_f32_16x16x32_bf16 v[92:95], v[156:159], v[208:211], v[92:95]
	v_mfma_f32_16x16x32_bf16 v[68:71], v[156:159], v[220:223], v[68:71]
	v_mfma_f32_16x16x32_bf16 v[68:71], v[160:163], v[230:233], v[68:71]
	v_mfma_f32_16x16x32_bf16 v[64:67], v[168:171], v[230:233], v[64:67]
	v_mfma_f32_16x16x32_bf16 v[64:67], v[164:167], v[220:223], v[64:67]
	v_mfma_f32_16x16x32_bf16 v[40:43], v[164:167], v[224:227], v[40:43]
	v_mfma_f32_16x16x32_bf16 v[40:43], v[168:171], v[234:237], v[40:43]
	v_mfma_f32_16x16x32_bf16 v[48:51], v[160:163], v[234:237], v[48:51]
	v_mfma_f32_16x16x32_bf16 v[48:51], v[156:159], v[224:227], v[48:51]
	s_setprio 0
	s_barrier
	s_add_i32 s39, s39, s68
	s_mov_b32 m0, s39
	ds_read_b128 v[172:175], v200 offset:49152
	ds_read_b128 v[208:211], v200 offset:51200
	ds_read_b128 v[212:215], v201 offset:49152
	ds_read_b128 v[216:219], v201 offset:51200
	ds_read_b128 v[220:223], v200 offset:53248
	ds_read_b128 v[224:227], v200 offset:55296
	ds_read_b128 v[230:233], v201 offset:53248
	ds_read_b128 v[234:237], v201 offset:55296
	s_add_u32 s98, s70, 0x80
	s_addc_u32 s99, s71, 0
	s_nop 0
	global_load_lds_dwordx4 v130, s[98:99]
	s_add_i32 m0, s39, 0x2000
	s_add_u32 s40, s70, 0x100080
	s_addc_u32 s41, s71, 0
	s_add_i32 s39, s48, s68
	global_load_lds_dwordx4 v134, s[98:99]
	s_mov_b32 m0, s39
	s_nop 0
	global_load_lds_dwordx4 v130, s[40:41]
	s_add_i32 m0, s39, 0x2000
	s_nop 0
	global_load_lds_dwordx4 v134, s[40:41]
	s_mov_b32 m0, s7
	s_nop 0
	s_add_u32 s98, s86, 0x80
	s_addc_u32 s99, s87, 0
	s_nop 0
	global_load_lds_dwordx4 v128, s[98:99]
	s_mov_b32 m0, s12
	s_nop 0
	global_load_lds_dwordx4 v132, s[98:99]
	s_waitcnt vmcnt(8)
	s_waitcnt lgkmcnt(0)
	s_waitcnt lgkmcnt(0)
	v_mfma_f32_16x16x32_bf16 v[28:31], v[140:143], v[172:175], v[28:31]
	v_mfma_f32_16x16x32_bf16 v[28:31], v[144:147], v[212:215], v[28:31]
	v_mfma_f32_16x16x32_bf16 v[24:27], v[152:155], v[212:215], v[24:27]
	v_mfma_f32_16x16x32_bf16 v[24:27], v[148:151], v[172:175], v[24:27]
	s_barrier
	s_setprio 3
	v_mfma_f32_16x16x32_bf16 v[16:19], v[148:151], v[208:211], v[16:19]
	v_mfma_f32_16x16x32_bf16 v[16:19], v[152:155], v[216:219], v[16:19]
	v_mfma_f32_16x16x32_bf16 v[20:23], v[144:147], v[216:219], v[20:23]
	v_mfma_f32_16x16x32_bf16 v[20:23], v[140:143], v[208:211], v[20:23]
	v_mfma_f32_16x16x32_bf16 v[12:15], v[140:143], v[220:223], v[12:15]
	v_mfma_f32_16x16x32_bf16 v[12:15], v[144:147], v[230:233], v[12:15]
	v_mfma_f32_16x16x32_bf16 v[8:11], v[152:155], v[230:233], v[8:11]
	v_mfma_f32_16x16x32_bf16 v[8:11], v[148:151], v[220:223], v[8:11]
	v_mfma_f32_16x16x32_bf16 v[0:3], v[148:151], v[224:227], v[0:3]
	v_mfma_f32_16x16x32_bf16 v[0:3], v[152:155], v[234:237], v[0:3]
	v_mfma_f32_16x16x32_bf16 v[4:7], v[144:147], v[234:237], v[4:7]
	v_mfma_f32_16x16x32_bf16 v[4:7], v[140:143], v[224:227], v[4:7]
	s_setprio 0
	s_setprio 3
	v_mfma_f32_16x16x32_bf16 v[80:83], v[156:159], v[172:175], v[80:83]
	v_mfma_f32_16x16x32_bf16 v[80:83], v[160:163], v[212:215], v[80:83]
	v_mfma_f32_16x16x32_bf16 v[72:75], v[168:171], v[212:215], v[72:75]
	v_mfma_f32_16x16x32_bf16 v[72:75], v[164:167], v[172:175], v[72:75]
	v_mfma_f32_16x16x32_bf16 v[56:59], v[164:167], v[208:211], v[56:59]
	v_mfma_f32_16x16x32_bf16 v[56:59], v[168:171], v[216:219], v[56:59]
	v_mfma_f32_16x16x32_bf16 v[60:63], v[160:163], v[216:219], v[60:63]
	v_mfma_f32_16x16x32_bf16 v[60:63], v[156:159], v[208:211], v[60:63]
	v_mfma_f32_16x16x32_bf16 v[52:55], v[156:159], v[220:223], v[52:55]
	v_mfma_f32_16x16x32_bf16 v[52:55], v[160:163], v[230:233], v[52:55]
	v_mfma_f32_16x16x32_bf16 v[44:47], v[168:171], v[230:233], v[44:47]
	v_mfma_f32_16x16x32_bf16 v[44:47], v[164:167], v[220:223], v[44:47]
	v_mfma_f32_16x16x32_bf16 v[32:35], v[164:167], v[224:227], v[32:35]
	v_mfma_f32_16x16x32_bf16 v[32:35], v[168:171], v[234:237], v[32:35]
	v_mfma_f32_16x16x32_bf16 v[36:39], v[160:163], v[234:237], v[36:39]
	v_mfma_f32_16x16x32_bf16 v[36:39], v[156:159], v[224:227], v[36:39]
	s_setprio 0
	s_barrier
	s_add_i32 s38, s38, 2
	s_add_u32 s84, s84, 0x100
	s_addc_u32 s85, s85, 0
	s_add_u32 s36, s36, 0x100
	s_addc_u32 s37, s37, 0
	s_cmp_gt_u32 s38, 61
	s_cbranch_scc0 .LBB0_417
	s_and_b64 vcc, exec, s[20:21]
	s_cbranch_vccz .LBB0_420
	s_barrier

; #define PG8_BAR __builtin_amdgcn_s_barrier()
; template <class Epi, class Sched, class GemmT>
; __device__ __forceinline__ void gemm_phase(LAS unsigned char* lds, const GemmT& g, const Sched& S, const Epi& E, const int wid) {
;     ...
;     Acc acc;
; #pragma unroll
;     for (int a = 0; a < 2; ++a)
; #pragma unroll
;         for (int b = 0; b < 2; ++b)
; #pragma unroll
;             for (int m = 0; m < 4; ++m)
; #pragma unroll
;                 for (int n = 0; n < 2; ++n) acc[a][b][m][n] = (f32x4){0.f, 0.f, 0.f, 0.f};
;     bf16x8 At[4][2], B0[2][2], B1[2][2];
;     const int sc8 = 0x7f7f7f7f; (void)sc8;
;     Seg cs = g.seg(cur, 0);
;     unsigned voffA[2], voffB[2]; size_t hstepA, hstepB;
;     PG8_VOFFS(voffA, voffB, hstepA, hstepB, cs);
;     const char* cA = cs.A; const char* cB = cs.B;
;     PG8_STAGE(PG8_SB(0, 0), cB, voffB); PG8_STAGE(PG8_SB(0, 1), cB + hstepB, voffB); PG8_STAGE(PG8_SA(0, 0), cA, voffA); PG8_STAGE(PG8_SA(0, 1), cA + hstepA, voffA);
;     if (wr == 1) PG8_BAR;
;     PG8_WAIT_V(2); PG8_BAR;
;     PG8_STAGE(PG8_SB(1, 0), cB + kstep, voffB); PG8_STAGE(PG8_SA(1, 0), cA + kstep, voffA); PG8_STAGE(PG8_SB(1, 1), cB + hstepB + kstep, voffB);
;     PG8_WAIT_V(6); PG8_BAR;
;     for (;;) {
;         const bool has_next = S.next(ui + 1, nxt);
; #pragma unroll 1
;         for (int sgi = 0; sgi < NSEG; ++sgi) {
;             const Seg ns = (sgi + 1 < NSEG) ? g.seg(cur, sgi + 1) : g.seg(has_next ? nxt : cur, 0);
;             unsigned nvA[2], nvB[2]; size_t nhA, nhB;
;             if constexpr (GemmT::UNIFORM) { nvA[0] = voffA[0]; nvA[1] = voffA[1]; nvB[0] = voffB[0]; nvB[1] = voffB[1]; nhA = hstepA; nhB = hstepB; }
;             else PG8_VOFFS(nvA, nvB, nhA, nhB, ns);
;             const int nt = cs.nt;
;             for (int t = 0; t < nt; t += 2) {
;                 const bool last = (t == nt - 2);
;                 const char* a1 = cA + (size_t)(t + 1) * kstep;
;                 const char* a2 = last ? ns.A : cA + (size_t)(t + 2) * kstep; const char* b2 = last ? ns.B : cB + (size_t)(t + 2) * kstep;
;                 const char* a3 = a2 + kstep; const char* b3 = b2 + kstep;
;                 unsigned vA2[2], vB2[2];
; #pragma unroll
;                 for (int i = 0; i < 2; ++i) { vA2[i] = last ? nvA[i] : voffA[i]; vB2[i] = last ? nvB[i] : voffB[i]; }
;                 const size_t hA2 = last ? nhA : hstepA, hB2 = last ? nhB : hstepB;
.LBB0_845:
	s_ashr_i32 s37, s36, 31
	s_ashr_i32 s39, s38, 31
	s_lshl_b64 s[36:37], s[36:37], 21
	s_add_u32 s36, s10, s36
	s_addc_u32 s37, s11, s37
	s_lshl_b64 s[38:39], s[38:39], 21
	s_add_u32 s41, s72, s38
	s_addc_u32 s59, s73, s39
	s_add_u32 s42, s42, 0x100080
	s_addc_u32 s43, s43, 0
	s_add_u32 s60, s52, s44
	v_mov_b32_e32 v0, 0
	s_addc_u32 s61, s53, s45
	s_mov_b32 s62, -2
	v_mov_b32_e32 v1, v0
	v_mov_b32_e32 v2, v0
	v_mov_b32_e32 v3, v0
	v_mov_b32_e32 v4, v0
	v_mov_b32_e32 v5, v0
	v_mov_b32_e32 v6, v0
	v_mov_b32_e32 v7, v0
	v_mov_b32_e32 v16, v0
	v_mov_b32_e32 v17, v0
	v_mov_b32_e32 v18, v0
	v_mov_b32_e32 v19, v0
	v_mov_b32_e32 v20, v0
	v_mov_b32_e32 v21, v0
	v_mov_b32_e32 v22, v0
	v_mov_b32_e32 v23, v0
	v_mov_b32_e32 v32, v0
	v_mov_b32_e32 v33, v0
	v_mov_b32_e32 v34, v0
	v_mov_b32_e32 v35, v0
	v_mov_b32_e32 v36, v0
	v_mov_b32_e32 v37, v0
	v_mov_b32_e32 v38, v0
	v_mov_b32_e32 v39, v0
	v_mov_b32_e32 v48, v0
	v_mov_b32_e32 v49, v0
	v_mov_b32_e32 v50, v0
	v_mov_b32_e32 v51, v0
	v_mov_b32_e32 v52, v0
	v_mov_b32_e32 v53, v0
	v_mov_b32_e32 v54, v0
	v_mov_b32_e32 v55, v0
	v_mov_b32_e32 v64, v0
	v_mov_b32_e32 v65, v0
	v_mov_b32_e32 v66, v0
	v_mov_b32_e32 v67, v0
	v_mov_b32_e32 v68, v0
	v_mov_b32_e32 v69, v0
	v_mov_b32_e32 v70, v0
	v_mov_b32_e32 v71, v0
	v_mov_b32_e32 v80, v0
	v_mov_b32_e32 v81, v0
	v_mov_b32_e32 v82, v0
	v_mov_b32_e32 v83, v0
	v_mov_b32_e32 v84, v0
	v_mov_b32_e32 v85, v0
	v_mov_b32_e32 v86, v0
	v_mov_b32_e32 v87, v0
	v_mov_b32_e32 v96, v0
	v_mov_b32_e32 v97, v0
	v_mov_b32_e32 v98, v0
	v_mov_b32_e32 v99, v0
	v_mov_b32_e32 v100, v0
	v_mov_b32_e32 v101, v0
	v_mov_b32_e32 v102, v0
	v_mov_b32_e32 v103, v0
	v_mov_b32_e32 v112, v0
	v_mov_b32_e32 v113, v0
	v_mov_b32_e32 v114, v0
	v_mov_b32_e32 v115, v0
	v_mov_b32_e32 v116, v0
	v_mov_b32_e32 v117, v0
	v_mov_b32_e32 v118, v0
	v_mov_b32_e32 v119, v0
	v_mov_b32_e32 v72, v0
	v_mov_b32_e32 v73, v0
	v_mov_b32_e32 v74, v0
	v_mov_b32_e32 v75, v0
	v_mov_b32_e32 v76, v0
	v_mov_b32_e32 v77, v0
	v_mov_b32_e32 v78, v0
	v_mov_b32_e32 v79, v0
	v_mov_b32_e32 v88, v0
	v_mov_b32_e32 v89, v0
	v_mov_b32_e32 v90, v0
	v_mov_b32_e32 v91, v0
	v_mov_b32_e32 v92, v0
	v_mov_b32_e32 v93, v0
	v_mov_b32_e32 v94, v0
	v_mov_b32_e32 v95, v0
	v_mov_b32_e32 v104, v0
	v_mov_b32_e32 v105, v0
	v_mov_b32_e32 v106, v0
	v_mov_b32_e32 v107, v0
	v_mov_b32_e32 v108, v0
	v_mov_b32_e32 v109, v0
	v_mov_b32_e32 v110, v0
	v_mov_b32_e32 v111, v0
	v_mov_b32_e32 v120, v0
	v_mov_b32_e32 v121, v0
	v_mov_b32_e32 v122, v0
	v_mov_b32_e32 v123, v0
	v_mov_b32_e32 v124, v0
	v_mov_b32_e32 v125, v0
	v_mov_b32_e32 v126, v0
	v_mov_b32_e32 v127, v0
	v_mov_b32_e32 v60, v0
	v_mov_b32_e32 v61, v0
	v_mov_b32_e32 v62, v0
	v_mov_b32_e32 v63, v0
	v_mov_b32_e32 v56, v0
	v_mov_b32_e32 v57, v0
	v_mov_b32_e32 v58, v0
	v_mov_b32_e32 v59, v0
	v_mov_b32_e32 v44, v0
	v_mov_b32_e32 v45, v0
	v_mov_b32_e32 v46, v0
	v_mov_b32_e32 v47, v0
	v_mov_b32_e32 v40, v0
	v_mov_b32_e32 v41, v0
	v_mov_b32_e32 v42, v0
	v_mov_b32_e32 v43, v0
	v_mov_b32_e32 v28, v0
	v_mov_b32_e32 v29, v0
	v_mov_b32_e32 v30, v0
	v_mov_b32_e32 v31, v0
	v_mov_b32_e32 v24, v0
	v_mov_b32_e32 v25, v0
	v_mov_b32_e32 v26, v0
	v_mov_b32_e32 v27, v0
	v_mov_b32_e32 v12, v0
	v_mov_b32_e32 v13, v0
	v_mov_b32_e32 v14, v0
	v_mov_b32_e32 v15, v0
	v_mov_b32_e32 v8, v0
	v_mov_b32_e32 v9, v0
	v_mov_b32_e32 v10, v0
	v_mov_b32_e32 v11, v0
	v_add_u32_e32 v188, 0x18000, v191
	v_add_u32_e32 v189, 0x18000, v192
	v_add_u32_e32 v224, 0x1c000, v191
	v_add_u32_e32 v225, 0x1c000, v192
.LBB0_846:
	ds_read_b128 v[128:131], v194
	ds_read_b128 v[132:135], v195
	ds_read_b128 v[136:139], v196
	ds_read_b128 v[140:143], v197
	ds_read_b128 v[144:147], v198
	ds_read_b128 v[148:151], v199
	ds_read_b128 v[152:155], v200
	ds_read_b128 v[168:171], v201
	s_add_u32 s44, s42, 0xfff00080
	s_addc_u32 s45, s43, -1
	s_cmp_eq_u32 s62, 60
	s_cselect_b32 s51, s37, s45
	s_cselect_b32 s50, s36, s44
	s_cselect_b32 s45, s59, s61
	s_cselect_b32 s44, s41, s60
	s_add_i32 m0, s14, 0xc000
	ds_read_b128 v[172:175], v202
	ds_read_b128 v[176:179], v202 offset:2048
	ds_read_b128 v[180:183], v203
	ds_read_b128 v[184:187], v203 offset:2048
	ds_read_b128 v[208:211], v202 offset:4096
	ds_read_b128 v[212:215], v202 offset:6144
	ds_read_b128 v[216:219], v203 offset:4096
	ds_read_b128 v[220:223], v203 offset:6144
	global_load_lds_dwordx4 v156, s[42:43]
	s_add_i32 m0, s14, 0xe000
	s_nop 0
	global_load_lds_dwordx4 v160, s[42:43]
	s_waitcnt vmcnt(8)
	s_waitcnt lgkmcnt(0)
	s_waitcnt lgkmcnt(0)
	v_mfma_f32_16x16x32_bf16 v[124:127], v[128:131], v[172:175], v[124:127]
	v_mfma_f32_16x16x32_bf16 v[124:127], v[132:135], v[180:183], v[124:127]
	v_mfma_f32_16x16x32_bf16 v[120:123], v[140:143], v[180:183], v[120:123]
	v_mfma_f32_16x16x32_bf16 v[120:123], v[136:139], v[172:175], v[120:123]
	s_barrier
; #define PG8_STAGE(bufoff, gbase, voff) do { _Pragma("unroll") for (int _i = 0; _i < 2; ++_i) \
;         __builtin_amdgcn_global_load_lds((const unsigned*)((const char*)(gbase) + (voff)[_i]), (LAS unsigned*)(lds + (bufoff) + ldsw + _i * 8192), 16, 0, 0); } while (0)
; #define PG8_LDA(dst, b, h) do { _Pragma("unroll") for (int m = 0; m < 4; ++m) _Pragma("unroll") for (int k = 0; k < 2; ++k) dst[m][k] = *(const LAS bf16x8*)(lds + PG8_SA(b, h) + aoffk[k] + m * 2048); } while (0)
; #define PG8_WAIT_V(n) asm volatile("s_waitcnt vmcnt(" #n ")" ::: "memory")
; #define PG8_WAIT_L(n) asm volatile("s_waitcnt lgkmcnt(" #n ")" ::: "memory")
; #define PG8_BAR __builtin_amdgcn_s_barrier()
; #define PG8_SCHED __builtin_amdgcn_sched_barrier(0)
; template <class Epi, class Sched, class GemmT>
; __device__ __forceinline__ void gemm_phase(LAS unsigned char* lds, const GemmT& g, const Sched& S, const Epi& E, const int wid) {
;     ...
;                 PG8_WAIT_V(8); PG8_WAIT_L(0); PG8_BAR; PG8_MMA(0, 0, At, B0); PG8_MMA(0, 1, At, B1); PG8_BAR; PG8_SCHED;
;                 PG8_LDA(At, 0, 1); PG8_STAGE(PG8_SB(0, 0), b2, vB2); PG8_STAGE(PG8_SB(0, 1), b2 + hB2, vB2); PG8_STAGE(PG8_SA(0, 0), a2, vA2);
;                 PG8_WAIT_V(8); PG8_WAIT_L(0); PG8_BAR; PG8_MMA(1, 0, At, B0); PG8_MMA(1, 1, At, B1); PG8_BAR; PG8_SCHED;
	s_setprio 3
	v_mfma_f32_16x16x32_bf16 v[104:107], v[136:139], v[176:179], v[104:107]
	v_mfma_f32_16x16x32_bf16 v[104:107], v[140:143], v[184:187], v[104:107]
	v_mfma_f32_16x16x32_bf16 v[108:111], v[132:135], v[184:187], v[108:111]
	v_mfma_f32_16x16x32_bf16 v[108:111], v[128:131], v[176:179], v[108:111]
	v_mfma_f32_16x16x32_bf16 v[92:95], v[128:131], v[208:211], v[92:95]
	v_mfma_f32_16x16x32_bf16 v[92:95], v[132:135], v[216:219], v[92:95]
	v_mfma_f32_16x16x32_bf16 v[88:91], v[140:143], v[216:219], v[88:91]
	v_mfma_f32_16x16x32_bf16 v[88:91], v[136:139], v[208:211], v[88:91]
	v_mfma_f32_16x16x32_bf16 v[72:75], v[136:139], v[212:215], v[72:75]
	v_mfma_f32_16x16x32_bf16 v[72:75], v[140:143], v[220:223], v[72:75]
	v_mfma_f32_16x16x32_bf16 v[76:79], v[132:135], v[220:223], v[76:79]
	v_mfma_f32_16x16x32_bf16 v[76:79], v[128:131], v[212:215], v[76:79]
	s_setprio 0
	s_setprio 3
	v_mfma_f32_16x16x32_bf16 v[116:119], v[144:147], v[172:175], v[116:119]
	v_mfma_f32_16x16x32_bf16 v[116:119], v[148:151], v[180:183], v[116:119]
	v_mfma_f32_16x16x32_bf16 v[112:115], v[168:171], v[180:183], v[112:115]
	v_mfma_f32_16x16x32_bf16 v[112:115], v[152:155], v[172:175], v[112:115]
	v_mfma_f32_16x16x32_bf16 v[96:99], v[152:155], v[176:179], v[96:99]
	v_mfma_f32_16x16x32_bf16 v[96:99], v[168:171], v[184:187], v[96:99]
	v_mfma_f32_16x16x32_bf16 v[100:103], v[148:151], v[184:187], v[100:103]
	v_mfma_f32_16x16x32_bf16 v[100:103], v[144:147], v[176:179], v[100:103]
	v_mfma_f32_16x16x32_bf16 v[84:87], v[144:147], v[208:211], v[84:87]
	v_mfma_f32_16x16x32_bf16 v[84:87], v[148:151], v[216:219], v[84:87]
	v_mfma_f32_16x16x32_bf16 v[80:83], v[168:171], v[216:219], v[80:83]
	v_mfma_f32_16x16x32_bf16 v[80:83], v[152:155], v[208:211], v[80:83]
	v_mfma_f32_16x16x32_bf16 v[64:67], v[152:155], v[212:215], v[64:67]
	v_mfma_f32_16x16x32_bf16 v[64:67], v[168:171], v[220:223], v[64:67]
	v_mfma_f32_16x16x32_bf16 v[68:71], v[148:151], v[220:223], v[68:71]
	v_mfma_f32_16x16x32_bf16 v[68:71], v[144:147], v[212:215], v[68:71]
	s_setprio 0
	s_barrier
	s_add_i32 s48, s54, s68
	s_mov_b32 m0, s48
	ds_read_b128 v[172:175], v202 offset:16384
	ds_read_b128 v[176:179], v202 offset:18432
	ds_read_b128 v[180:183], v203 offset:16384
	ds_read_b128 v[184:187], v203 offset:18432
	ds_read_b128 v[208:211], v202 offset:20480
	ds_read_b128 v[212:215], v202 offset:22528
	ds_read_b128 v[216:219], v203 offset:20480
	ds_read_b128 v[220:223], v203 offset:22528
	global_load_lds_dwordx4 v158, s[44:45]
	s_add_i32 m0, s48, 0x2000
	s_add_u32 s48, s44, 0x100000
	s_addc_u32 s49, s45, 0
	s_add_i32 s63, s55, s68
	global_load_lds_dwordx4 v162, s[44:45]
	s_mov_b32 m0, s63
	s_nop 0
	global_load_lds_dwordx4 v158, s[48:49]
	s_add_i32 m0, s63, 0x2000
	s_nop 0
	global_load_lds_dwordx4 v162, s[48:49]
	s_mov_b32 m0, s14
	s_nop 0
	global_load_lds_dwordx4 v156, s[50:51]
	s_mov_b32 m0, s15
	s_nop 0
	global_load_lds_dwordx4 v160, s[50:51]
	s_waitcnt vmcnt(8)
	s_waitcnt lgkmcnt(0)
	s_waitcnt lgkmcnt(0)
	v_mfma_f32_16x16x32_bf16 v[52:55], v[128:131], v[172:175], v[52:55]
	v_mfma_f32_16x16x32_bf16 v[52:55], v[132:135], v[180:183], v[52:55]
	v_mfma_f32_16x16x32_bf16 v[48:51], v[140:143], v[180:183], v[48:51]
	v_mfma_f32_16x16x32_bf16 v[48:51], v[136:139], v[172:175], v[48:51]
	s_barrier
	s_setprio 3
	v_mfma_f32_16x16x32_bf16 v[32:35], v[136:139], v[176:179], v[32:35]
	v_mfma_f32_16x16x32_bf16 v[32:35], v[140:143], v[184:187], v[32:35]
	v_mfma_f32_16x16x32_bf16 v[36:39], v[132:135], v[184:187], v[36:39]
	v_mfma_f32_16x16x32_bf16 v[36:39], v[128:131], v[176:179], v[36:39]
	v_mfma_f32_16x16x32_bf16 v[20:23], v[128:131], v[208:211], v[20:23]
	v_mfma_f32_16x16x32_bf16 v[20:23], v[132:135], v[216:219], v[20:23]
	v_mfma_f32_16x16x32_bf16 v[16:19], v[140:143], v[216:219], v[16:19]
	v_mfma_f32_16x16x32_bf16 v[16:19], v[136:139], v[208:211], v[16:19]
	v_mfma_f32_16x16x32_bf16 v[0:3], v[136:139], v[212:215], v[0:3]
	v_mfma_f32_16x16x32_bf16 v[0:3], v[140:143], v[220:223], v[0:3]
	v_mfma_f32_16x16x32_bf16 v[4:7], v[132:135], v[220:223], v[4:7]
	v_mfma_f32_16x16x32_bf16 v[4:7], v[128:131], v[212:215], v[4:7]
	s_setprio 0
	s_setprio 3
	v_mfma_f32_16x16x32_bf16 v[60:63], v[144:147], v[172:175], v[60:63]
	v_mfma_f32_16x16x32_bf16 v[60:63], v[148:151], v[180:183], v[60:63]
	v_mfma_f32_16x16x32_bf16 v[56:59], v[168:171], v[180:183], v[56:59]
	v_mfma_f32_16x16x32_bf16 v[56:59], v[152:155], v[172:175], v[56:59]
	v_mfma_f32_16x16x32_bf16 v[40:43], v[152:155], v[176:179], v[40:43]
	v_mfma_f32_16x16x32_bf16 v[40:43], v[168:171], v[184:187], v[40:43]
	v_mfma_f32_16x16x32_bf16 v[44:47], v[148:151], v[184:187], v[44:47]
	v_mfma_f32_16x16x32_bf16 v[44:47], v[144:147], v[176:179], v[44:47]
	v_mfma_f32_16x16x32_bf16 v[28:31], v[144:147], v[208:211], v[28:31]
	v_mfma_f32_16x16x32_bf16 v[28:31], v[148:151], v[216:219], v[28:31]
	v_mfma_f32_16x16x32_bf16 v[24:27], v[168:171], v[216:219], v[24:27]
	v_mfma_f32_16x16x32_bf16 v[24:27], v[152:155], v[208:211], v[24:27]
	v_mfma_f32_16x16x32_bf16 v[8:11], v[152:155], v[212:215], v[8:11]
	v_mfma_f32_16x16x32_bf16 v[8:11], v[168:171], v[220:223], v[8:11]
	v_mfma_f32_16x16x32_bf16 v[12:15], v[148:151], v[220:223], v[12:15]
	v_mfma_f32_16x16x32_bf16 v[12:15], v[144:147], v[212:215], v[12:15]
	s_setprio 0
	s_barrier
; #define PG8_STAGE(bufoff, gbase, voff) do { _Pragma("unroll") for (int _i = 0; _i < 2; ++_i) \
;         __builtin_amdgcn_global_load_lds((const unsigned*)((const char*)(gbase) + (voff)[_i]), (LAS unsigned*)(lds + (bufoff) + ldsw + _i * 8192), 16, 0, 0); } while (0)
; #define PG8_LDA(dst, b, h) do { _Pragma("unroll") for (int m = 0; m < 4; ++m) _Pragma("unroll") for (int k = 0; k < 2; ++k) dst[m][k] = *(const LAS bf16x8*)(lds + PG8_SA(b, h) + aoffk[k] + m * 2048); } while (0)
; #define PG8_LDB(dst, b, h) do { _Pragma("unroll") for (int n = 0; n < 2; ++n) _Pragma("unroll") for (int k = 0; k < 2; ++k) dst[n][k] = *(const LAS bf16x8*)(lds + PG8_SB(b, h) + boffk[k] + n * 2048); } while (0)
; #define PG8_WAIT_V(n) asm volatile("s_waitcnt vmcnt(" #n ")" ::: "memory")
; #define PG8_WAIT_L(n) asm volatile("s_waitcnt lgkmcnt(" #n ")" ::: "memory")
; #define PG8_BAR __builtin_amdgcn_s_barrier()
; #define PG8_SCHED __builtin_amdgcn_sched_barrier(0)
; template <class Epi, class Sched, class GemmT>
; __device__ __forceinline__ void gemm_phase(LAS unsigned char* lds, const GemmT& g, const Sched& S, const Epi& E, const int wid) {
;     ...
;                 PG8_LDB(B0, 1, 0); PG8_LDB(B1, 1, 1); PG8_SCHED; PG8_LDA(At, 1, 0); PG8_STAGE(PG8_SA(0, 1), a2 + hA2, vA2);
;                 PG8_WAIT_V(8); PG8_WAIT_L(0); PG8_BAR; PG8_MMA(0, 0, At, B0); PG8_MMA(0, 1, At, B1); PG8_BAR; PG8_SCHED;
;                 PG8_LDA(At, 1, 1); PG8_STAGE(PG8_SB(1, 0), b3, vB2); PG8_STAGE(PG8_SB(1, 1), b3 + hB2, vB2); PG8_STAGE(PG8_SA(1, 0), a3, vA2);
;                 PG8_WAIT_V(8); PG8_WAIT_L(0); PG8_BAR; PG8_MMA(1, 0, At, B0); PG8_MMA(1, 1, At, B1); PG8_BAR; PG8_SCHED;
;             }
	s_add_i32 s63, 0, 0x18000
	s_add_i32 s64, 0, 0x1c000
	ds_read_b128 v[128:131], v188
	ds_read_b128 v[132:135], v189
	ds_read_b128 v[136:139], v204
	ds_read_b128 v[140:143], v205
	ds_read_b128 v[144:147], v224
	ds_read_b128 v[148:151], v225
	ds_read_b128 v[152:155], v206
	ds_read_b128 v[168:171], v207
	s_add_u32 s48, s50, 0x100000
	s_addc_u32 s49, s51, 0
	s_mov_b32 m0, s22
	ds_read_b128 v[172:175], v202 offset:32768
	ds_read_b128 v[176:179], v202 offset:34816
	ds_read_b128 v[180:183], v203 offset:32768
	ds_read_b128 v[184:187], v203 offset:34816
	ds_read_b128 v[208:211], v202 offset:36864
	ds_read_b128 v[212:215], v202 offset:38912
	ds_read_b128 v[216:219], v203 offset:36864
	ds_read_b128 v[220:223], v203 offset:38912
	global_load_lds_dwordx4 v156, s[48:49]
	s_mov_b32 m0, s23
	s_nop 0
	global_load_lds_dwordx4 v160, s[48:49]
	s_waitcnt vmcnt(8)
	s_waitcnt lgkmcnt(0)
	s_waitcnt lgkmcnt(0)
	v_mfma_f32_16x16x32_bf16 v[124:127], v[128:131], v[172:175], v[124:127]
	v_mfma_f32_16x16x32_bf16 v[124:127], v[132:135], v[180:183], v[124:127]
	v_mfma_f32_16x16x32_bf16 v[120:123], v[140:143], v[180:183], v[120:123]
	v_mfma_f32_16x16x32_bf16 v[120:123], v[136:139], v[172:175], v[120:123]
	s_barrier
	s_setprio 3
	v_mfma_f32_16x16x32_bf16 v[104:107], v[136:139], v[176:179], v[104:107]
	v_mfma_f32_16x16x32_bf16 v[104:107], v[140:143], v[184:187], v[104:107]
	v_mfma_f32_16x16x32_bf16 v[108:111], v[132:135], v[184:187], v[108:111]
	v_mfma_f32_16x16x32_bf16 v[108:111], v[128:131], v[176:179], v[108:111]
	v_mfma_f32_16x16x32_bf16 v[92:95], v[128:131], v[208:211], v[92:95]
	v_mfma_f32_16x16x32_bf16 v[92:95], v[132:135], v[216:219], v[92:95]
	v_mfma_f32_16x16x32_bf16 v[88:91], v[140:143], v[216:219], v[88:91]
	v_mfma_f32_16x16x32_bf16 v[88:91], v[136:139], v[208:211], v[88:91]
	v_mfma_f32_16x16x32_bf16 v[72:75], v[136:139], v[212:215], v[72:75]
	v_mfma_f32_16x16x32_bf16 v[72:75], v[140:143], v[220:223], v[72:75]
	v_mfma_f32_16x16x32_bf16 v[76:79], v[132:135], v[220:223], v[76:79]
	v_mfma_f32_16x16x32_bf16 v[76:79], v[128:131], v[212:215], v[76:79]
	s_setprio 0
	s_setprio 3
	v_mfma_f32_16x16x32_bf16 v[116:119], v[144:147], v[172:175], v[116:119]
	v_mfma_f32_16x16x32_bf16 v[116:119], v[148:151], v[180:183], v[116:119]
	v_mfma_f32_16x16x32_bf16 v[112:115], v[168:171], v[180:183], v[112:115]
	v_mfma_f32_16x16x32_bf16 v[112:115], v[152:155], v[172:175], v[112:115]
	v_mfma_f32_16x16x32_bf16 v[96:99], v[152:155], v[176:179], v[96:99]
	v_mfma_f32_16x16x32_bf16 v[96:99], v[168:171], v[184:187], v[96:99]
	v_mfma_f32_16x16x32_bf16 v[100:103], v[148:151], v[184:187], v[100:103]
	v_mfma_f32_16x16x32_bf16 v[100:103], v[144:147], v[176:179], v[100:103]
	v_mfma_f32_16x16x32_bf16 v[84:87], v[144:147], v[208:211], v[84:87]
	v_mfma_f32_16x16x32_bf16 v[84:87], v[148:151], v[216:219], v[84:87]
	v_mfma_f32_16x16x32_bf16 v[80:83], v[168:171], v[216:219], v[80:83]
	v_mfma_f32_16x16x32_bf16 v[80:83], v[152:155], v[208:211], v[80:83]
	v_mfma_f32_16x16x32_bf16 v[64:67], v[152:155], v[212:215], v[64:67]
	v_mfma_f32_16x16x32_bf16 v[64:67], v[168:171], v[220:223], v[64:67]
	v_mfma_f32_16x16x32_bf16 v[68:71], v[148:151], v[220:223], v[68:71]
	v_mfma_f32_16x16x32_bf16 v[68:71], v[144:147], v[212:215], v[68:71]
	s_setprio 0
	s_barrier
	s_add_i32 s48, s63, s68
	s_mov_b32 m0, s48
	ds_read_b128 v[172:175], v202 offset:49152
	ds_read_b128 v[176:179], v202 offset:51200
	ds_read_b128 v[180:183], v203 offset:49152
	ds_read_b128 v[184:187], v203 offset:51200
	ds_read_b128 v[208:211], v202 offset:53248
	ds_read_b128 v[212:215], v202 offset:55296
	ds_read_b128 v[216:219], v203 offset:53248
	ds_read_b128 v[220:223], v203 offset:55296
	s_add_u32 s98, s44, 0x80
	s_addc_u32 s99, s45, 0
	s_nop 0
	global_load_lds_dwordx4 v158, s[98:99]
	s_add_i32 m0, s48, 0x2000
	s_add_u32 s44, s44, 0x100080
	s_addc_u32 s45, s45, 0
	s_add_i32 s48, s64, s68
	global_load_lds_dwordx4 v162, s[98:99]
	s_mov_b32 m0, s48
	s_nop 0
	global_load_lds_dwordx4 v158, s[44:45]
	s_add_i32 m0, s48, 0x2000
	s_nop 0
	global_load_lds_dwordx4 v162, s[44:45]
	s_mov_b32 m0, s34
	s_nop 0
	s_add_u32 s98, s50, 0x80
	s_addc_u32 s99, s51, 0
	s_nop 0
	global_load_lds_dwordx4 v156, s[98:99]
	s_mov_b32 m0, s35
	s_nop 0
	global_load_lds_dwordx4 v160, s[98:99]
	s_waitcnt vmcnt(8)
	s_waitcnt lgkmcnt(0)
	s_waitcnt lgkmcnt(0)
	v_mfma_f32_16x16x32_bf16 v[52:55], v[128:131], v[172:175], v[52:55]
	v_mfma_f32_16x16x32_bf16 v[52:55], v[132:135], v[180:183], v[52:55]
	v_mfma_f32_16x16x32_bf16 v[48:51], v[140:143], v[180:183], v[48:51]
	v_mfma_f32_16x16x32_bf16 v[48:51], v[136:139], v[172:175], v[48:51]
	s_barrier
	s_setprio 3
	v_mfma_f32_16x16x32_bf16 v[32:35], v[136:139], v[176:179], v[32:35]
	v_mfma_f32_16x16x32_bf16 v[32:35], v[140:143], v[184:187], v[32:35]
	v_mfma_f32_16x16x32_bf16 v[36:39], v[132:135], v[184:187], v[36:39]
	v_mfma_f32_16x16x32_bf16 v[36:39], v[128:131], v[176:179], v[36:39]
	v_mfma_f32_16x16x32_bf16 v[20:23], v[128:131], v[208:211], v[20:23]
	v_mfma_f32_16x16x32_bf16 v[20:23], v[132:135], v[216:219], v[20:23]
	v_mfma_f32_16x16x32_bf16 v[16:19], v[140:143], v[216:219], v[16:19]
	v_mfma_f32_16x16x32_bf16 v[16:19], v[136:139], v[208:211], v[16:19]
	v_mfma_f32_16x16x32_bf16 v[0:3], v[136:139], v[212:215], v[0:3]
	v_mfma_f32_16x16x32_bf16 v[0:3], v[140:143], v[220:223], v[0:3]
	v_mfma_f32_16x16x32_bf16 v[4:7], v[132:135], v[220:223], v[4:7]
	v_mfma_f32_16x16x32_bf16 v[4:7], v[128:131], v[212:215], v[4:7]
	s_setprio 0
	s_setprio 3
	v_mfma_f32_16x16x32_bf16 v[60:63], v[144:147], v[172:175], v[60:63]
	v_mfma_f32_16x16x32_bf16 v[60:63], v[148:151], v[180:183], v[60:63]
	v_mfma_f32_16x16x32_bf16 v[56:59], v[168:171], v[180:183], v[56:59]
	v_mfma_f32_16x16x32_bf16 v[56:59], v[152:155], v[172:175], v[56:59]
	v_mfma_f32_16x16x32_bf16 v[40:43], v[152:155], v[176:179], v[40:43]
	v_mfma_f32_16x16x32_bf16 v[40:43], v[168:171], v[184:187], v[40:43]
	v_mfma_f32_16x16x32_bf16 v[44:47], v[148:151], v[184:187], v[44:47]
	v_mfma_f32_16x16x32_bf16 v[44:47], v[144:147], v[176:179], v[44:47]
	v_mfma_f32_16x16x32_bf16 v[28:31], v[144:147], v[208:211], v[28:31]
	v_mfma_f32_16x16x32_bf16 v[28:31], v[148:151], v[216:219], v[28:31]
	v_mfma_f32_16x16x32_bf16 v[24:27], v[168:171], v[216:219], v[24:27]
	v_mfma_f32_16x16x32_bf16 v[24:27], v[152:155], v[208:211], v[24:27]
	v_mfma_f32_16x16x32_bf16 v[8:11], v[152:155], v[212:215], v[8:11]
	v_mfma_f32_16x16x32_bf16 v[8:11], v[168:171], v[220:223], v[8:11]
	v_mfma_f32_16x16x32_bf16 v[12:15], v[148:151], v[220:223], v[12:15]
	v_mfma_f32_16x16x32_bf16 v[12:15], v[144:147], v[212:215], v[12:15]
	s_setprio 0
	s_barrier
	s_add_i32 s62, s62, 2
	s_add_u32 s42, s42, 0x100
	s_addc_u32 s43, s43, 0
	s_add_u32 s60, s60, 0x100
	s_addc_u32 s61, s61, 0
	s_cmp_gt_u32 s62, 61
	s_cbranch_scc0 .LBB0_846
	s_and_b64 vcc, exec, s[20:21]
	s_cbranch_vccz .LBB0_849
	s_barrier

; #define PG8_BAR __builtin_amdgcn_s_barrier()
; template <class Epi, class Sched, class GemmT>
; __device__ __forceinline__ void gemm_phase(LAS unsigned char* lds, const GemmT& g, const Sched& S, const Epi& E, const int wid) {
;     ...
;     Acc acc;
; #pragma unroll
;     for (int a = 0; a < 2; ++a)
; #pragma unroll
;         for (int b = 0; b < 2; ++b)
; #pragma unroll
;             for (int m = 0; m < 4; ++m)
; #pragma unroll
;                 for (int n = 0; n < 2; ++n) acc[a][b][m][n] = (f32x4){0.f, 0.f, 0.f, 0.f};
;     bf16x8 At[4][2], B0[2][2], B1[2][2];
;     const int sc8 = 0x7f7f7f7f; (void)sc8;
;     Seg cs = g.seg(cur, 0);
;     unsigned voffA[2], voffB[2]; size_t hstepA, hstepB;
;     PG8_VOFFS(voffA, voffB, hstepA, hstepB, cs);
;     const char* cA = cs.A; const char* cB = cs.B;
;     PG8_STAGE(PG8_SB(0, 0), cB, voffB); PG8_STAGE(PG8_SB(0, 1), cB + hstepB, voffB); PG8_STAGE(PG8_SA(0, 0), cA, voffA); PG8_STAGE(PG8_SA(0, 1), cA + hstepA, voffA);
;     if (wr == 1) PG8_BAR;
;     PG8_WAIT_V(2); PG8_BAR;
;     PG8_STAGE(PG8_SB(1, 0), cB + kstep, voffB); PG8_STAGE(PG8_SA(1, 0), cA + kstep, voffA); PG8_STAGE(PG8_SB(1, 1), cB + hstepB + kstep, voffB);
;     PG8_WAIT_V(6); PG8_BAR;
;     for (;;) {
;         const bool has_next = S.next(ui + 1, nxt);
; #pragma unroll 1
;         for (int sgi = 0; sgi < NSEG; ++sgi) {
;             const Seg ns = (sgi + 1 < NSEG) ? g.seg(cur, sgi + 1) : g.seg(has_next ? nxt : cur, 0);
;             unsigned nvA[2], nvB[2]; size_t nhA, nhB;
;             if constexpr (GemmT::UNIFORM) { nvA[0] = voffA[0]; nvA[1] = voffA[1]; nvB[0] = voffB[0]; nvB[1] = voffB[1]; nhA = hstepA; nhB = hstepB; }
;             else PG8_VOFFS(nvA, nvB, nhA, nhB, ns);
;             const int nt = cs.nt;
;             for (int t = 0; t < nt; t += 2) {
;                 const bool last = (t == nt - 2);
;                 const char* a1 = cA + (size_t)(t + 1) * kstep;
;                 const char* a2 = last ? ns.A : cA + (size_t)(t + 2) * kstep; const char* b2 = last ? ns.B : cB + (size_t)(t + 2) * kstep;
;                 const char* a3 = a2 + kstep; const char* b3 = b2 + kstep;
;                 unsigned vA2[2], vB2[2];
; #pragma unroll
;                 for (int i = 0; i < 2; ++i) { vA2[i] = last ? nvA[i] : voffA[i]; vB2[i] = last ? nvB[i] : voffB[i]; }
;                 const size_t hA2 = last ? nhA : hstepA, hB2 = last ? nhB : hstepB;
.LBB0_935:
	s_ashr_i32 s57, s56, 31
	s_ashr_i32 s59, s58, 31
	s_lshl_b64 s[56:57], s[56:57], 21
	s_add_u32 s56, s46, s56
	s_addc_u32 s57, s47, s57
	s_lshl_b64 s[58:59], s[58:59], 21
	s_add_u32 s63, s86, s58
	s_addc_u32 s77, s87, s59
	s_add_u32 s64, s64, 0x100080
	s_addc_u32 s65, s65, 0
	s_add_u32 s78, s48, s66
	v_mov_b32_e32 v24, 0
	s_addc_u32 s79, s49, s67
	s_mov_b32 s81, -2
	v_mov_b32_e32 v25, v24
	v_mov_b32_e32 v26, v24
	v_mov_b32_e32 v27, v24
	v_mov_b32_e32 v64, v24
	v_mov_b32_e32 v65, v24
	v_mov_b32_e32 v66, v24
	v_mov_b32_e32 v67, v24
	v_mov_b32_e32 v88, v24
	v_mov_b32_e32 v89, v24
	v_mov_b32_e32 v90, v24
	v_mov_b32_e32 v91, v24
	v_mov_b32_e32 v28, v24
	v_mov_b32_e32 v29, v24
	v_mov_b32_e32 v30, v24
	v_mov_b32_e32 v31, v24
	v_mov_b32_e32 v100, v24
	v_mov_b32_e32 v101, v24
	v_mov_b32_e32 v102, v24
	v_mov_b32_e32 v103, v24
	v_mov_b32_e32 v36, v24
	v_mov_b32_e32 v37, v24
	v_mov_b32_e32 v38, v24
	v_mov_b32_e32 v39, v24
	v_mov_b32_e32 v108, v24
	v_mov_b32_e32 v109, v24
	v_mov_b32_e32 v110, v24
	v_mov_b32_e32 v111, v24
	v_mov_b32_e32 v56, v24
	v_mov_b32_e32 v57, v24
	v_mov_b32_e32 v58, v24
	v_mov_b32_e32 v59, v24
	v_mov_b32_e32 v80, v24
	v_mov_b32_e32 v81, v24
	v_mov_b32_e32 v82, v24
	v_mov_b32_e32 v83, v24
	v_mov_b32_e32 v84, v24
	v_mov_b32_e32 v85, v24
	v_mov_b32_e32 v86, v24
	v_mov_b32_e32 v87, v24
	v_mov_b32_e32 v16, v24
	v_mov_b32_e32 v17, v24
	v_mov_b32_e32 v18, v24
	v_mov_b32_e32 v19, v24
	v_mov_b32_e32 v72, v24
	v_mov_b32_e32 v73, v24
	v_mov_b32_e32 v74, v24
	v_mov_b32_e32 v75, v24
	v_mov_b32_e32 v20, v24
	v_mov_b32_e32 v21, v24
	v_mov_b32_e32 v22, v24
	v_mov_b32_e32 v23, v24
	v_mov_b32_e32 v76, v24
	v_mov_b32_e32 v77, v24
	v_mov_b32_e32 v78, v24
	v_mov_b32_e32 v79, v24
	v_mov_b32_e32 v60, v24
	v_mov_b32_e32 v61, v24
	v_mov_b32_e32 v62, v24
	v_mov_b32_e32 v63, v24
	v_mov_b32_e32 v68, v24
	v_mov_b32_e32 v69, v24
	v_mov_b32_e32 v70, v24
	v_mov_b32_e32 v71, v24
	v_mov_b32_e32 v92, v24
	v_mov_b32_e32 v93, v24
	v_mov_b32_e32 v94, v24
	v_mov_b32_e32 v95, v24
	v_mov_b32_e32 v112, v24
	v_mov_b32_e32 v113, v24
	v_mov_b32_e32 v114, v24
	v_mov_b32_e32 v115, v24
	v_mov_b32_e32 v96, v24
	v_mov_b32_e32 v97, v24
	v_mov_b32_e32 v98, v24
	v_mov_b32_e32 v99, v24
	v_mov_b32_e32 v32, v24
	v_mov_b32_e32 v33, v24
	v_mov_b32_e32 v34, v24
	v_mov_b32_e32 v35, v24
	v_mov_b32_e32 v104, v24
	v_mov_b32_e32 v105, v24
	v_mov_b32_e32 v106, v24
	v_mov_b32_e32 v107, v24
	v_mov_b32_e32 v40, v24
	v_mov_b32_e32 v41, v24
	v_mov_b32_e32 v42, v24
	v_mov_b32_e32 v43, v24
	v_mov_b32_e32 v120, v24
	v_mov_b32_e32 v121, v24
	v_mov_b32_e32 v122, v24
	v_mov_b32_e32 v123, v24
	v_mov_b32_e32 v124, v24
	v_mov_b32_e32 v125, v24
	v_mov_b32_e32 v126, v24
	v_mov_b32_e32 v127, v24
	v_mov_b32_e32 v44, v24
	v_mov_b32_e32 v45, v24
	v_mov_b32_e32 v46, v24
	v_mov_b32_e32 v47, v24
	v_mov_b32_e32 v0, v24
	v_mov_b32_e32 v1, v24
	v_mov_b32_e32 v2, v24
	v_mov_b32_e32 v3, v24
	v_mov_b32_e32 v48, v24
	v_mov_b32_e32 v49, v24
	v_mov_b32_e32 v50, v24
	v_mov_b32_e32 v51, v24
	v_mov_b32_e32 v4, v24
	v_mov_b32_e32 v5, v24
	v_mov_b32_e32 v6, v24
	v_mov_b32_e32 v7, v24
	v_mov_b32_e32 v52, v24
	v_mov_b32_e32 v53, v24
	v_mov_b32_e32 v54, v24
	v_mov_b32_e32 v55, v24
	v_mov_b32_e32 v8, v24
	v_mov_b32_e32 v9, v24
	v_mov_b32_e32 v10, v24
	v_mov_b32_e32 v11, v24
	v_mov_b32_e32 v116, v24
	v_mov_b32_e32 v117, v24
	v_mov_b32_e32 v118, v24
	v_mov_b32_e32 v119, v24
	v_mov_b32_e32 v128, v24
	v_mov_b32_e32 v129, v24
	v_mov_b32_e32 v130, v24
	v_mov_b32_e32 v131, v24
	v_add_u32_e32 v204, 0x18000, v210
	v_add_u32_e32 v205, 0x18000, v211
	v_add_u32_e32 v206, 0x1c000, v210
	v_add_u32_e32 v207, 0x1c000, v211
.LBB0_936:
	ds_read_b128 v[12:15], v223
	ds_read_b128 v[132:135], v224
	ds_read_b128 v[136:139], v225
	ds_read_b128 v[140:143], v226
	ds_read_b128 v[144:147], v227
	ds_read_b128 v[148:151], v229
	ds_read_b128 v[152:155], v230
	ds_read_b128 v[156:159], v231
	s_add_u32 s66, s64, 0xfff00080
	s_addc_u32 s67, s65, -1
	s_cmp_eq_u32 s81, 60
	s_cselect_b32 s71, s57, s67
	s_cselect_b32 s70, s56, s66
	s_cselect_b32 s67, s77, s79
	s_cselect_b32 s66, s63, s78
	s_add_i32 m0, s14, 0xc000
	ds_read_b128 v[160:163], v232
	ds_read_b128 v[164:167], v232 offset:2048
	ds_read_b128 v[168:171], v233
	ds_read_b128 v[172:175], v233 offset:2048
	ds_read_b128 v[188:191], v232 offset:4096
	ds_read_b128 v[192:195], v232 offset:6144
	ds_read_b128 v[196:199], v233 offset:4096
	ds_read_b128 v[200:203], v233 offset:6144
	global_load_lds_dwordx4 v176, s[64:65]
	s_add_i32 m0, s14, 0xe000
	s_nop 0
	global_load_lds_dwordx4 v180, s[64:65]
	s_waitcnt vmcnt(8)
	s_waitcnt lgkmcnt(0)
	s_waitcnt lgkmcnt(0)
	v_mfma_f32_16x16x32_bf16 v[124:127], v[12:15], v[160:163], v[124:127]
	v_mfma_f32_16x16x32_bf16 v[124:127], v[132:135], v[168:171], v[124:127]
	v_mfma_f32_16x16x32_bf16 v[120:123], v[140:143], v[168:171], v[120:123]
	v_mfma_f32_16x16x32_bf16 v[120:123], v[136:139], v[160:163], v[120:123]
	s_barrier
; #define PG8_STAGE(bufoff, gbase, voff) do { _Pragma("unroll") for (int _i = 0; _i < 2; ++_i) \
;         __builtin_amdgcn_global_load_lds((const unsigned*)((const char*)(gbase) + (voff)[_i]), (LAS unsigned*)(lds + (bufoff) + ldsw + _i * 8192), 16, 0, 0); } while (0)
; #define PG8_LDA(dst, b, h) do { _Pragma("unroll") for (int m = 0; m < 4; ++m) _Pragma("unroll") for (int k = 0; k < 2; ++k) dst[m][k] = *(const LAS bf16x8*)(lds + PG8_SA(b, h) + aoffk[k] + m * 2048); } while (0)
; #define PG8_WAIT_V(n) asm volatile("s_waitcnt vmcnt(" #n ")" ::: "memory")
; #define PG8_WAIT_L(n) asm volatile("s_waitcnt lgkmcnt(" #n ")" ::: "memory")
; #define PG8_BAR __builtin_amdgcn_s_barrier()
; #define PG8_SCHED __builtin_amdgcn_sched_barrier(0)
; template <class Epi, class Sched, class GemmT>
; __device__ __forceinline__ void gemm_phase(LAS unsigned char* lds, const GemmT& g, const Sched& S, const Epi& E, const int wid) {
;     ...
;                 PG8_WAIT_V(8); PG8_WAIT_L(0); PG8_BAR; PG8_MMA(0, 0, At, B0); PG8_MMA(0, 1, At, B1); PG8_BAR; PG8_SCHED;
;                 PG8_LDA(At, 0, 1); PG8_STAGE(PG8_SB(0, 0), b2, vB2); PG8_STAGE(PG8_SB(0, 1), b2 + hB2, vB2); PG8_STAGE(PG8_SA(0, 0), a2, vA2);
;                 PG8_WAIT_V(8); PG8_WAIT_L(0); PG8_BAR; PG8_MMA(1, 0, At, B0); PG8_MMA(1, 1, At, B1); PG8_BAR; PG8_SCHED;
	s_setprio 3
	v_mfma_f32_16x16x32_bf16 v[104:107], v[136:139], v[164:167], v[104:107]
	v_mfma_f32_16x16x32_bf16 v[104:107], v[140:143], v[172:175], v[104:107]
	v_mfma_f32_16x16x32_bf16 v[40:43], v[132:135], v[172:175], v[40:43]
	v_mfma_f32_16x16x32_bf16 v[40:43], v[12:15], v[164:167], v[40:43]
	v_mfma_f32_16x16x32_bf16 v[32:35], v[12:15], v[188:191], v[32:35]
	v_mfma_f32_16x16x32_bf16 v[32:35], v[132:135], v[196:199], v[32:35]
	v_mfma_f32_16x16x32_bf16 v[96:99], v[140:143], v[196:199], v[96:99]
	v_mfma_f32_16x16x32_bf16 v[96:99], v[136:139], v[188:191], v[96:99]
	v_mfma_f32_16x16x32_bf16 v[92:95], v[136:139], v[192:195], v[92:95]
	v_mfma_f32_16x16x32_bf16 v[92:95], v[140:143], v[200:203], v[92:95]
	v_mfma_f32_16x16x32_bf16 v[112:115], v[132:135], v[200:203], v[112:115]
	v_mfma_f32_16x16x32_bf16 v[112:115], v[12:15], v[192:195], v[112:115]
	s_setprio 0
	s_setprio 3
	v_mfma_f32_16x16x32_bf16 v[68:71], v[144:147], v[160:163], v[68:71]
	v_mfma_f32_16x16x32_bf16 v[68:71], v[148:151], v[168:171], v[68:71]
	v_mfma_f32_16x16x32_bf16 v[60:63], v[156:159], v[168:171], v[60:63]
	v_mfma_f32_16x16x32_bf16 v[60:63], v[152:155], v[160:163], v[60:63]
	v_mfma_f32_16x16x32_bf16 v[20:23], v[152:155], v[164:167], v[20:23]
	v_mfma_f32_16x16x32_bf16 v[20:23], v[156:159], v[172:175], v[20:23]
	v_mfma_f32_16x16x32_bf16 v[76:79], v[148:151], v[172:175], v[76:79]
	v_mfma_f32_16x16x32_bf16 v[76:79], v[144:147], v[164:167], v[76:79]
	v_mfma_f32_16x16x32_bf16 v[72:75], v[144:147], v[188:191], v[72:75]
	v_mfma_f32_16x16x32_bf16 v[72:75], v[148:151], v[196:199], v[72:75]
	v_mfma_f32_16x16x32_bf16 v[16:19], v[156:159], v[196:199], v[16:19]
	v_mfma_f32_16x16x32_bf16 v[16:19], v[152:155], v[188:191], v[16:19]
	v_mfma_f32_16x16x32_bf16 v[80:83], v[152:155], v[192:195], v[80:83]
	v_mfma_f32_16x16x32_bf16 v[80:83], v[156:159], v[200:203], v[80:83]
	v_mfma_f32_16x16x32_bf16 v[84:87], v[148:151], v[200:203], v[84:87]
	v_mfma_f32_16x16x32_bf16 v[84:87], v[144:147], v[192:195], v[84:87]
	s_setprio 0
	s_barrier
	s_add_i32 s80, s69, s68
	s_mov_b32 m0, s80
	ds_read_b128 v[160:163], v232 offset:16384
	ds_read_b128 v[164:167], v232 offset:18432
	ds_read_b128 v[168:171], v233 offset:16384
	ds_read_b128 v[172:175], v233 offset:18432
	ds_read_b128 v[188:191], v232 offset:20480
	ds_read_b128 v[192:195], v232 offset:22528
	ds_read_b128 v[196:199], v233 offset:20480
	ds_read_b128 v[200:203], v233 offset:22528
	global_load_lds_dwordx4 v178, s[66:67]
	s_add_i32 m0, s80, 0x2000
	s_add_u32 s82, s66, 0x100000
	s_addc_u32 s83, s67, 0
	s_add_i32 s80, s72, s68
	global_load_lds_dwordx4 v182, s[66:67]
	s_mov_b32 m0, s80
	s_nop 0
	global_load_lds_dwordx4 v178, s[82:83]
	s_add_i32 m0, s80, 0x2000
	s_nop 0
	global_load_lds_dwordx4 v182, s[82:83]
	s_mov_b32 m0, s14
	s_nop 0
	s_add_u32 s100, s70, 0x80
	s_addc_u32 s101, s71, 0
	global_load_lds_dwordx4 v176, s[70:71]
	s_mov_b32 m0, s15
	s_nop 0
	global_load_lds_dwordx4 v180, s[70:71]
	s_waitcnt vmcnt(8)
	s_waitcnt lgkmcnt(0)
	s_waitcnt lgkmcnt(0)
	v_mfma_f32_16x16x32_bf16 v[56:59], v[12:15], v[160:163], v[56:59]
	v_mfma_f32_16x16x32_bf16 v[56:59], v[132:135], v[168:171], v[56:59]
	v_mfma_f32_16x16x32_bf16 v[108:111], v[136:139], v[160:163], v[108:111]
	v_mfma_f32_16x16x32_bf16 v[108:111], v[140:143], v[168:171], v[108:111]
	s_barrier
	s_setprio 3
	v_mfma_f32_16x16x32_bf16 v[36:39], v[12:15], v[164:167], v[36:39]
	v_mfma_f32_16x16x32_bf16 v[36:39], v[132:135], v[172:175], v[36:39]
	v_mfma_f32_16x16x32_bf16 v[100:103], v[136:139], v[164:167], v[100:103]
	v_mfma_f32_16x16x32_bf16 v[100:103], v[140:143], v[172:175], v[100:103]
	v_mfma_f32_16x16x32_bf16 v[28:31], v[12:15], v[188:191], v[28:31]
	v_mfma_f32_16x16x32_bf16 v[28:31], v[132:135], v[196:199], v[28:31]
	v_mfma_f32_16x16x32_bf16 v[88:91], v[136:139], v[188:191], v[88:91]
	v_mfma_f32_16x16x32_bf16 v[88:91], v[140:143], v[196:199], v[88:91]
	v_mfma_f32_16x16x32_bf16 v[24:27], v[136:139], v[192:195], v[24:27]
	v_mfma_f32_16x16x32_bf16 v[24:27], v[140:143], v[200:203], v[24:27]
	v_mfma_f32_16x16x32_bf16 v[12:15], v[12:15], v[192:195], v[64:67]
	v_mfma_f32_16x16x32_bf16 v[12:15], v[132:135], v[200:203], v[12:15]
	s_setprio 0
	s_setprio 3
	v_mfma_f32_16x16x32_bf16 v[64:67], v[144:147], v[192:195], v[116:119]
	v_mfma_f32_16x16x32_bf16 v[116:119], v[148:151], v[200:203], v[64:67]
	v_mfma_f32_16x16x32_bf16 v[44:47], v[144:147], v[160:163], v[44:47]
	v_mfma_f32_16x16x32_bf16 v[44:47], v[148:151], v[168:171], v[44:47]
	v_mfma_f32_16x16x32_bf16 v[0:3], v[152:155], v[160:163], v[0:3]
	v_mfma_f32_16x16x32_bf16 v[0:3], v[156:159], v[168:171], v[0:3]
	v_mfma_f32_16x16x32_bf16 v[48:51], v[144:147], v[164:167], v[48:51]
	v_mfma_f32_16x16x32_bf16 v[48:51], v[148:151], v[172:175], v[48:51]
	v_mfma_f32_16x16x32_bf16 v[4:7], v[152:155], v[164:167], v[4:7]
	v_mfma_f32_16x16x32_bf16 v[4:7], v[156:159], v[172:175], v[4:7]
	v_mfma_f32_16x16x32_bf16 v[64:67], v[152:155], v[192:195], v[128:131]
	v_mfma_f32_16x16x32_bf16 v[128:131], v[156:159], v[200:203], v[64:67]
	v_mfma_f32_16x16x32_bf16 v[52:55], v[144:147], v[188:191], v[52:55]
	v_mfma_f32_16x16x32_bf16 v[52:55], v[148:151], v[196:199], v[52:55]
	v_mfma_f32_16x16x32_bf16 v[8:11], v[152:155], v[188:191], v[8:11]
	v_mfma_f32_16x16x32_bf16 v[8:11], v[156:159], v[196:199], v[8:11]
	s_setprio 0
	s_barrier
; #define PG8_STAGE(bufoff, gbase, voff) do { _Pragma("unroll") for (int _i = 0; _i < 2; ++_i) \
;         __builtin_amdgcn_global_load_lds((const unsigned*)((const char*)(gbase) + (voff)[_i]), (LAS unsigned*)(lds + (bufoff) + ldsw + _i * 8192), 16, 0, 0); } while (0)
; #define PG8_LDA(dst, b, h) do { _Pragma("unroll") for (int m = 0; m < 4; ++m) _Pragma("unroll") for (int k = 0; k < 2; ++k) dst[m][k] = *(const LAS bf16x8*)(lds + PG8_SA(b, h) + aoffk[k] + m * 2048); } while (0)
; #define PG8_LDB(dst, b, h) do { _Pragma("unroll") for (int n = 0; n < 2; ++n) _Pragma("unroll") for (int k = 0; k < 2; ++k) dst[n][k] = *(const LAS bf16x8*)(lds + PG8_SB(b, h) + boffk[k] + n * 2048); } while (0)
; #define PG8_WAIT_V(n) asm volatile("s_waitcnt vmcnt(" #n ")" ::: "memory")
; #define PG8_WAIT_L(n) asm volatile("s_waitcnt lgkmcnt(" #n ")" ::: "memory")
; #define PG8_BAR __builtin_amdgcn_s_barrier()
; #define PG8_SCHED __builtin_amdgcn_sched_barrier(0)
; template <class Epi, class Sched, class GemmT>
; __device__ __forceinline__ void gemm_phase(LAS unsigned char* lds, const GemmT& g, const Sched& S, const Epi& E, const int wid) {
;     ...
;                 PG8_LDB(B0, 1, 0); PG8_LDB(B1, 1, 1); PG8_SCHED; PG8_LDA(At, 1, 0); PG8_STAGE(PG8_SA(0, 1), a2 + hA2, vA2);
;                 PG8_WAIT_V(8); PG8_WAIT_L(0); PG8_BAR; PG8_MMA(0, 0, At, B0); PG8_MMA(0, 1, At, B1); PG8_BAR; PG8_SCHED;
;                 PG8_LDA(At, 1, 1); PG8_STAGE(PG8_SB(1, 0), b3, vB2); PG8_STAGE(PG8_SB(1, 1), b3 + hB2, vB2); PG8_STAGE(PG8_SA(1, 0), a3, vA2);
;                 PG8_WAIT_V(8); PG8_WAIT_L(0); PG8_BAR; PG8_MMA(1, 0, At, B0); PG8_MMA(1, 1, At, B1); PG8_BAR; PG8_SCHED;
;             }
	s_add_i32 s80, 0, 0x18000
	s_add_i32 s82, 0, 0x1c000
	ds_read_b128 v[64:67], v204
	ds_read_b128 v[132:135], v205
	ds_read_b128 v[136:139], v234
	ds_read_b128 v[140:143], v235
	ds_read_b128 v[144:147], v206
	ds_read_b128 v[148:151], v207
	ds_read_b128 v[152:155], v236
	ds_read_b128 v[156:159], v237
	s_add_u32 s70, s70, 0x100000
	s_addc_u32 s71, s71, 0
	s_mov_b32 m0, s23
	ds_read_b128 v[160:163], v232 offset:32768
	ds_read_b128 v[164:167], v232 offset:34816
	ds_read_b128 v[168:171], v233 offset:32768
	ds_read_b128 v[172:175], v233 offset:34816
	ds_read_b128 v[188:191], v232 offset:36864
	ds_read_b128 v[192:195], v232 offset:38912
	ds_read_b128 v[196:199], v233 offset:36864
	ds_read_b128 v[200:203], v233 offset:38912
	global_load_lds_dwordx4 v176, s[70:71]
	s_mov_b32 m0, s34
	s_nop 0
	global_load_lds_dwordx4 v180, s[70:71]
	s_waitcnt vmcnt(8)
	s_waitcnt lgkmcnt(0)
	s_waitcnt lgkmcnt(0)
	v_mfma_f32_16x16x32_bf16 v[124:127], v[64:67], v[160:163], v[124:127]
	v_mfma_f32_16x16x32_bf16 v[124:127], v[132:135], v[168:171], v[124:127]
	v_mfma_f32_16x16x32_bf16 v[120:123], v[140:143], v[168:171], v[120:123]
	v_mfma_f32_16x16x32_bf16 v[120:123], v[136:139], v[160:163], v[120:123]
	s_barrier
	s_setprio 3
	v_mfma_f32_16x16x32_bf16 v[104:107], v[136:139], v[164:167], v[104:107]
	v_mfma_f32_16x16x32_bf16 v[104:107], v[140:143], v[172:175], v[104:107]
	v_mfma_f32_16x16x32_bf16 v[40:43], v[132:135], v[172:175], v[40:43]
	v_mfma_f32_16x16x32_bf16 v[40:43], v[64:67], v[164:167], v[40:43]
	v_mfma_f32_16x16x32_bf16 v[32:35], v[64:67], v[188:191], v[32:35]
	v_mfma_f32_16x16x32_bf16 v[32:35], v[132:135], v[196:199], v[32:35]
	v_mfma_f32_16x16x32_bf16 v[96:99], v[140:143], v[196:199], v[96:99]
	v_mfma_f32_16x16x32_bf16 v[96:99], v[136:139], v[188:191], v[96:99]
	v_mfma_f32_16x16x32_bf16 v[92:95], v[136:139], v[192:195], v[92:95]
	v_mfma_f32_16x16x32_bf16 v[92:95], v[140:143], v[200:203], v[92:95]
	v_mfma_f32_16x16x32_bf16 v[112:115], v[132:135], v[200:203], v[112:115]
	v_mfma_f32_16x16x32_bf16 v[112:115], v[64:67], v[192:195], v[112:115]
	s_setprio 0
	s_setprio 3
	v_mfma_f32_16x16x32_bf16 v[68:71], v[144:147], v[160:163], v[68:71]
	v_mfma_f32_16x16x32_bf16 v[68:71], v[148:151], v[168:171], v[68:71]
	v_mfma_f32_16x16x32_bf16 v[60:63], v[156:159], v[168:171], v[60:63]
	v_mfma_f32_16x16x32_bf16 v[60:63], v[152:155], v[160:163], v[60:63]
	v_mfma_f32_16x16x32_bf16 v[20:23], v[152:155], v[164:167], v[20:23]
	v_mfma_f32_16x16x32_bf16 v[20:23], v[156:159], v[172:175], v[20:23]
	v_mfma_f32_16x16x32_bf16 v[76:79], v[148:151], v[172:175], v[76:79]
	v_mfma_f32_16x16x32_bf16 v[76:79], v[144:147], v[164:167], v[76:79]
	v_mfma_f32_16x16x32_bf16 v[72:75], v[144:147], v[188:191], v[72:75]
	v_mfma_f32_16x16x32_bf16 v[72:75], v[148:151], v[196:199], v[72:75]
	v_mfma_f32_16x16x32_bf16 v[16:19], v[156:159], v[196:199], v[16:19]
	v_mfma_f32_16x16x32_bf16 v[16:19], v[152:155], v[188:191], v[16:19]
	v_mfma_f32_16x16x32_bf16 v[80:83], v[152:155], v[192:195], v[80:83]
	v_mfma_f32_16x16x32_bf16 v[80:83], v[156:159], v[200:203], v[80:83]
	v_mfma_f32_16x16x32_bf16 v[84:87], v[148:151], v[200:203], v[84:87]
	v_mfma_f32_16x16x32_bf16 v[84:87], v[144:147], v[192:195], v[84:87]
	s_setprio 0
	s_barrier
	s_add_i32 s70, s80, s68
	s_mov_b32 m0, s70
	ds_read_b128 v[160:163], v232 offset:49152
	ds_read_b128 v[164:167], v232 offset:51200
	ds_read_b128 v[168:171], v233 offset:49152
	ds_read_b128 v[172:175], v233 offset:51200
	ds_read_b128 v[188:191], v232 offset:53248
	ds_read_b128 v[192:195], v232 offset:55296
	ds_read_b128 v[196:199], v233 offset:53248
	ds_read_b128 v[200:203], v233 offset:55296
	s_add_u32 s98, s66, 0x80
	s_addc_u32 s99, s67, 0
	s_nop 0
	global_load_lds_dwordx4 v178, s[98:99]
	s_add_i32 m0, s70, 0x2000
	s_add_u32 s66, s66, 0x100080
	s_addc_u32 s67, s67, 0
	s_add_i32 s70, s82, s68
	global_load_lds_dwordx4 v182, s[98:99]
	s_mov_b32 m0, s70
	s_nop 0
	global_load_lds_dwordx4 v178, s[66:67]
	s_add_i32 m0, s70, 0x2000
	s_nop 0
	global_load_lds_dwordx4 v182, s[66:67]
	s_mov_b32 m0, s54
	s_nop 0
	global_load_lds_dwordx4 v176, s[100:101]
	s_mov_b32 m0, s55
	s_nop 0
	global_load_lds_dwordx4 v180, s[100:101]
	s_waitcnt vmcnt(8)
	s_waitcnt lgkmcnt(0)
	s_waitcnt lgkmcnt(0)
	v_mfma_f32_16x16x32_bf16 v[12:15], v[64:67], v[192:195], v[12:15]
	v_mfma_f32_16x16x32_bf16 v[56:59], v[64:67], v[160:163], v[56:59]
	v_mfma_f32_16x16x32_bf16 v[56:59], v[132:135], v[168:171], v[56:59]
	v_mfma_f32_16x16x32_bf16 v[108:111], v[136:139], v[160:163], v[108:111]
	s_barrier
	s_setprio 3
	v_mfma_f32_16x16x32_bf16 v[108:111], v[140:143], v[168:171], v[108:111]
	v_mfma_f32_16x16x32_bf16 v[36:39], v[64:67], v[164:167], v[36:39]
	v_mfma_f32_16x16x32_bf16 v[36:39], v[132:135], v[172:175], v[36:39]
	v_mfma_f32_16x16x32_bf16 v[100:103], v[136:139], v[164:167], v[100:103]
	v_mfma_f32_16x16x32_bf16 v[100:103], v[140:143], v[172:175], v[100:103]
	v_mfma_f32_16x16x32_bf16 v[28:31], v[64:67], v[188:191], v[28:31]
	v_mfma_f32_16x16x32_bf16 v[28:31], v[132:135], v[196:199], v[28:31]
	v_mfma_f32_16x16x32_bf16 v[88:91], v[136:139], v[188:191], v[88:91]
	v_mfma_f32_16x16x32_bf16 v[88:91], v[140:143], v[196:199], v[88:91]
	v_mfma_f32_16x16x32_bf16 v[64:67], v[132:135], v[200:203], v[12:15]
	v_mfma_f32_16x16x32_bf16 v[12:15], v[136:139], v[192:195], v[24:27]
	v_mfma_f32_16x16x32_bf16 v[24:27], v[140:143], v[200:203], v[12:15]
	s_setprio 0
	s_setprio 3
	v_mfma_f32_16x16x32_bf16 v[12:15], v[144:147], v[160:163], v[44:47]
	v_mfma_f32_16x16x32_bf16 v[44:47], v[148:151], v[168:171], v[12:15]
	v_mfma_f32_16x16x32_bf16 v[0:3], v[152:155], v[160:163], v[0:3]
	v_mfma_f32_16x16x32_bf16 v[0:3], v[156:159], v[168:171], v[0:3]
	v_mfma_f32_16x16x32_bf16 v[4:7], v[152:155], v[164:167], v[4:7]
	v_mfma_f32_16x16x32_bf16 v[4:7], v[156:159], v[172:175], v[4:7]
	v_mfma_f32_16x16x32_bf16 v[12:15], v[144:147], v[164:167], v[48:51]
	v_mfma_f32_16x16x32_bf16 v[48:51], v[148:151], v[172:175], v[12:15]
	v_mfma_f32_16x16x32_bf16 v[8:11], v[152:155], v[188:191], v[8:11]
	v_mfma_f32_16x16x32_bf16 v[8:11], v[156:159], v[196:199], v[8:11]
	v_mfma_f32_16x16x32_bf16 v[12:15], v[144:147], v[188:191], v[52:55]
	v_mfma_f32_16x16x32_bf16 v[52:55], v[148:151], v[196:199], v[12:15]
	v_mfma_f32_16x16x32_bf16 v[12:15], v[144:147], v[192:195], v[116:119]
	v_mfma_f32_16x16x32_bf16 v[116:119], v[148:151], v[200:203], v[12:15]
	v_mfma_f32_16x16x32_bf16 v[12:15], v[152:155], v[192:195], v[128:131]
	v_mfma_f32_16x16x32_bf16 v[128:131], v[156:159], v[200:203], v[12:15]
	s_setprio 0
	s_barrier
	s_add_i32 s81, s81, 2
	s_add_u32 s64, s64, 0x100
	s_addc_u32 s65, s65, 0
	s_add_u32 s78, s78, 0x100
	s_addc_u32 s79, s79, 0
	s_cmp_gt_u32 s81, 61
	s_cbranch_scc0 .LBB0_936
	s_and_b64 vcc, exec, s[40:41]
	s_cbranch_vccz .LBB0_939
	s_barrier

; #define PG8_STAGE(bufoff, gbase, voff) do { _Pragma("unroll") for (int _i = 0; _i < 2; ++_i) \
;         __builtin_amdgcn_global_load_lds((const unsigned*)((const char*)(gbase) + (voff)[_i]), (LAS unsigned*)(lds + (bufoff) + ldsw + _i * 8192), 16, 0, 0); } while (0)
; #define PG8_LDA(dst, b, h) do { _Pragma("unroll") for (int m = 0; m < 4; ++m) _Pragma("unroll") for (int k = 0; k < 2; ++k) dst[m][k] = *(const LAS bf16x8*)(lds + PG8_SA(b, h) + aoffk[k] + m * 2048); } while (0)
; #define PG8_LDB(dst, b, h) do { _Pragma("unroll") for (int n = 0; n < 2; ++n) _Pragma("unroll") for (int k = 0; k < 2; ++k) dst[n][k] = *(const LAS bf16x8*)(lds + PG8_SB(b, h) + boffk[k] + n * 2048); } while (0)
; #define PG8_WAIT_V(n) asm volatile("s_waitcnt vmcnt(" #n ")" ::: "memory")
; #define PG8_WAIT_L(n) asm volatile("s_waitcnt lgkmcnt(" #n ")" ::: "memory")
; #define PG8_BAR __builtin_amdgcn_s_barrier()
; #define PG8_SCHED __builtin_amdgcn_sched_barrier(0)
; template <class Epi, class Sched, class GemmT>
; __device__ __forceinline__ void gemm_phase(LAS unsigned char* lds, const GemmT& g, const Sched& S, const Epi& E, const int wid) {
;     ...
;                 PG8_LDB(B0, 0, 0); PG8_LDB(B1, 0, 1); PG8_SCHED; PG8_LDA(At, 0, 0); PG8_STAGE(PG8_SA(1, 1), a1 + hstepA, voffA);
;                 PG8_WAIT_V(8); PG8_WAIT_L(0); PG8_BAR; PG8_MMA(0, 0, At, B0); PG8_MMA(0, 1, At, B1); PG8_BAR; PG8_SCHED;
;     ...
;         for (int a = 0; a < 2; ++a)
; #pragma unroll
;             for (int b = 0; b < 2; ++b)
; #pragma unroll
;                 for (int m = 0; m < 4; ++m)
; #pragma unroll
;                     for (int n = 0; n < 2; ++n) acc[a][b][m][n] = (f32x4){0.f, 0.f, 0.f, 0.f};
.LBB0_1095:
	s_mul_i32 s18, s19, 0x560000
	s_mul_hi_i32 s21, s19, 0x560000
	s_add_u32 s18, s12, s18
	s_addc_u32 s19, s13, s21
	s_mul_hi_i32 s21, s20, 0x560000
	s_mul_i32 s20, s20, 0x560000
	s_add_u32 s52, s84, s20
	s_addc_u32 s53, s85, s21
	s_add_u32 s22, s22, 0x2b0080
	s_addc_u32 s23, s23, 0
	s_add_u32 s54, s30, s24
	v_mov_b32_e32 v0, 0
	s_addc_u32 s55, s31, s25
	s_mov_b32 s56, -2
	v_mov_b32_e32 v1, v0
	v_mov_b32_e32 v2, v0
	v_mov_b32_e32 v3, v0
	v_mov_b32_e32 v4, v0
	v_mov_b32_e32 v5, v0
	v_mov_b32_e32 v6, v0
	v_mov_b32_e32 v7, v0
	v_mov_b32_e32 v8, v0
	v_mov_b32_e32 v9, v0
	v_mov_b32_e32 v10, v0
	v_mov_b32_e32 v11, v0
	v_mov_b32_e32 v20, v0
	v_mov_b32_e32 v21, v0
	v_mov_b32_e32 v22, v0
	v_mov_b32_e32 v23, v0
	v_mov_b32_e32 v32, v0
	v_mov_b32_e32 v33, v0
	v_mov_b32_e32 v34, v0
	v_mov_b32_e32 v35, v0
	v_mov_b32_e32 v36, v0
	v_mov_b32_e32 v37, v0
	v_mov_b32_e32 v38, v0
	v_mov_b32_e32 v39, v0
	v_mov_b32_e32 v48, v0
	v_mov_b32_e32 v49, v0
	v_mov_b32_e32 v50, v0
	v_mov_b32_e32 v51, v0
	v_mov_b32_e32 v52, v0
	v_mov_b32_e32 v53, v0
	v_mov_b32_e32 v54, v0
	v_mov_b32_e32 v55, v0
	v_mov_b32_e32 v60, v0
	v_mov_b32_e32 v61, v0
	v_mov_b32_e32 v62, v0
	v_mov_b32_e32 v63, v0
	v_mov_b32_e32 v68, v0
	v_mov_b32_e32 v69, v0
	v_mov_b32_e32 v70, v0
	v_mov_b32_e32 v71, v0
	v_mov_b32_e32 v76, v0
	v_mov_b32_e32 v77, v0
	v_mov_b32_e32 v78, v0
	v_mov_b32_e32 v79, v0
	v_mov_b32_e32 v84, v0
	v_mov_b32_e32 v85, v0
	v_mov_b32_e32 v86, v0
	v_mov_b32_e32 v87, v0
	v_mov_b32_e32 v92, v0
	v_mov_b32_e32 v93, v0
	v_mov_b32_e32 v94, v0
	v_mov_b32_e32 v95, v0
	v_mov_b32_e32 v100, v0
	v_mov_b32_e32 v101, v0
	v_mov_b32_e32 v102, v0
	v_mov_b32_e32 v103, v0
	v_mov_b32_e32 v108, v0
	v_mov_b32_e32 v109, v0
	v_mov_b32_e32 v110, v0
	v_mov_b32_e32 v111, v0
	v_mov_b32_e32 v116, v0
	v_mov_b32_e32 v117, v0
	v_mov_b32_e32 v118, v0
	v_mov_b32_e32 v119, v0
	v_mov_b32_e32 v72, v0
	v_mov_b32_e32 v73, v0
	v_mov_b32_e32 v74, v0
	v_mov_b32_e32 v75, v0
	v_mov_b32_e32 v80, v0
	v_mov_b32_e32 v81, v0
	v_mov_b32_e32 v82, v0
	v_mov_b32_e32 v83, v0
	v_mov_b32_e32 v88, v0
	v_mov_b32_e32 v89, v0
	v_mov_b32_e32 v90, v0
	v_mov_b32_e32 v91, v0
	v_mov_b32_e32 v96, v0
	v_mov_b32_e32 v97, v0
	v_mov_b32_e32 v98, v0
	v_mov_b32_e32 v99, v0
	v_mov_b32_e32 v104, v0
	v_mov_b32_e32 v105, v0
	v_mov_b32_e32 v106, v0
	v_mov_b32_e32 v107, v0
	v_mov_b32_e32 v112, v0
	v_mov_b32_e32 v113, v0
	v_mov_b32_e32 v114, v0
	v_mov_b32_e32 v115, v0
	v_mov_b32_e32 v120, v0
	v_mov_b32_e32 v121, v0
	v_mov_b32_e32 v122, v0
	v_mov_b32_e32 v123, v0
	v_mov_b32_e32 v124, v0
	v_mov_b32_e32 v125, v0
	v_mov_b32_e32 v126, v0
	v_mov_b32_e32 v127, v0
	v_mov_b32_e32 v64, v0
	v_mov_b32_e32 v65, v0
	v_mov_b32_e32 v66, v0
	v_mov_b32_e32 v67, v0
	v_mov_b32_e32 v56, v0
	v_mov_b32_e32 v57, v0
	v_mov_b32_e32 v58, v0
	v_mov_b32_e32 v59, v0
	v_mov_b32_e32 v44, v0
	v_mov_b32_e32 v45, v0
	v_mov_b32_e32 v46, v0
	v_mov_b32_e32 v47, v0
	v_mov_b32_e32 v40, v0
	v_mov_b32_e32 v41, v0
	v_mov_b32_e32 v42, v0
	v_mov_b32_e32 v43, v0
	v_mov_b32_e32 v28, v0
	v_mov_b32_e32 v29, v0
	v_mov_b32_e32 v30, v0
	v_mov_b32_e32 v31, v0
	v_mov_b32_e32 v24, v0
	v_mov_b32_e32 v25, v0
	v_mov_b32_e32 v26, v0
	v_mov_b32_e32 v27, v0
	v_mov_b32_e32 v16, v0
	v_mov_b32_e32 v17, v0
	v_mov_b32_e32 v18, v0
	v_mov_b32_e32 v19, v0
	v_mov_b32_e32 v12, v0
	v_mov_b32_e32 v13, v0
	v_mov_b32_e32 v14, v0
	v_mov_b32_e32 v15, v0
	v_add_u32_e32 v222, 0x18000, v185
	v_add_u32_e32 v223, 0x18000, v186
	v_add_u32_e32 v224, 0x1c000, v185
	v_add_u32_e32 v225, 0x1c000, v186
.LBB0_1096:
	ds_read_b128 v[128:131], v188
	ds_read_b128 v[132:135], v189
	ds_read_b128 v[136:139], v190
	ds_read_b128 v[140:143], v191
	ds_read_b128 v[144:147], v192
	ds_read_b128 v[148:151], v193
	ds_read_b128 v[152:155], v194
	ds_read_b128 v[156:159], v195
	s_add_u32 s24, s22, 0xffd50080
	s_addc_u32 s25, s23, -1
	s_cmpk_eq_i32 s56, 0xa8
	s_cselect_b32 s27, s19, s25
	s_cselect_b32 s26, s18, s24
	s_cselect_b32 s25, s53, s55
	s_cselect_b32 s24, s52, s54
	s_add_i32 m0, s34, 0xc000
	ds_read_b128 v[160:163], v196
	ds_read_b128 v[164:167], v196 offset:2048
	ds_read_b128 v[180:183], v197
	ds_read_b128 v[202:205], v197 offset:2048
	ds_read_b128 v[206:209], v196 offset:4096
	ds_read_b128 v[210:213], v196 offset:6144
	ds_read_b128 v[214:217], v197 offset:4096
	ds_read_b128 v[218:221], v197 offset:6144
	global_load_lds_dwordx4 v168, s[22:23]
	s_add_i32 m0, s34, 0xe000
	s_nop 0
	global_load_lds_dwordx4 v172, s[22:23]
	s_waitcnt vmcnt(8)
	s_waitcnt lgkmcnt(0)
	s_waitcnt lgkmcnt(0)
	v_mfma_f32_16x16x32_bf16 v[124:127], v[128:131], v[160:163], v[124:127]
	v_mfma_f32_16x16x32_bf16 v[124:127], v[132:135], v[180:183], v[124:127]
	v_mfma_f32_16x16x32_bf16 v[120:123], v[140:143], v[180:183], v[120:123]
	v_mfma_f32_16x16x32_bf16 v[120:123], v[136:139], v[160:163], v[120:123]
	s_barrier
; #define PG8_STAGE(bufoff, gbase, voff) do { _Pragma("unroll") for (int _i = 0; _i < 2; ++_i) \
;         __builtin_amdgcn_global_load_lds((const unsigned*)((const char*)(gbase) + (voff)[_i]), (LAS unsigned*)(lds + (bufoff) + ldsw + _i * 8192), 16, 0, 0); } while (0)
; #define PG8_LDA(dst, b, h) do { _Pragma("unroll") for (int m = 0; m < 4; ++m) _Pragma("unroll") for (int k = 0; k < 2; ++k) dst[m][k] = *(const LAS bf16x8*)(lds + PG8_SA(b, h) + aoffk[k] + m * 2048); } while (0)
; #define PG8_WAIT_V(n) asm volatile("s_waitcnt vmcnt(" #n ")" ::: "memory")
; #define PG8_WAIT_L(n) asm volatile("s_waitcnt lgkmcnt(" #n ")" ::: "memory")
; #define PG8_BAR __builtin_amdgcn_s_barrier()
; #define PG8_SCHED __builtin_amdgcn_sched_barrier(0)
; template <class Epi, class Sched, class GemmT>
; __device__ __forceinline__ void gemm_phase(LAS unsigned char* lds, const GemmT& g, const Sched& S, const Epi& E, const int wid) {
;     ...
;                 PG8_WAIT_V(8); PG8_WAIT_L(0); PG8_BAR; PG8_MMA(0, 0, At, B0); PG8_MMA(0, 1, At, B1); PG8_BAR; PG8_SCHED;
;                 PG8_LDA(At, 0, 1); PG8_STAGE(PG8_SB(0, 0), b2, vB2); PG8_STAGE(PG8_SB(0, 1), b2 + hB2, vB2); PG8_STAGE(PG8_SA(0, 0), a2, vA2);
;                 PG8_WAIT_V(8); PG8_WAIT_L(0); PG8_BAR; PG8_MMA(1, 0, At, B0); PG8_MMA(1, 1, At, B1); PG8_BAR; PG8_SCHED;
	s_setprio 3
	v_mfma_f32_16x16x32_bf16 v[104:107], v[136:139], v[164:167], v[104:107]
	v_mfma_f32_16x16x32_bf16 v[104:107], v[140:143], v[202:205], v[104:107]
	v_mfma_f32_16x16x32_bf16 v[112:115], v[132:135], v[202:205], v[112:115]
	v_mfma_f32_16x16x32_bf16 v[112:115], v[128:131], v[164:167], v[112:115]
	v_mfma_f32_16x16x32_bf16 v[96:99], v[128:131], v[206:209], v[96:99]
	v_mfma_f32_16x16x32_bf16 v[96:99], v[132:135], v[214:217], v[96:99]
	v_mfma_f32_16x16x32_bf16 v[88:91], v[140:143], v[214:217], v[88:91]
	v_mfma_f32_16x16x32_bf16 v[88:91], v[136:139], v[206:209], v[88:91]
	v_mfma_f32_16x16x32_bf16 v[72:75], v[136:139], v[210:213], v[72:75]
	v_mfma_f32_16x16x32_bf16 v[72:75], v[140:143], v[218:221], v[72:75]
	v_mfma_f32_16x16x32_bf16 v[80:83], v[132:135], v[218:221], v[80:83]
	v_mfma_f32_16x16x32_bf16 v[80:83], v[128:131], v[210:213], v[80:83]
	s_setprio 0
	s_setprio 3
	v_mfma_f32_16x16x32_bf16 v[116:119], v[144:147], v[160:163], v[116:119]
	v_mfma_f32_16x16x32_bf16 v[116:119], v[148:151], v[180:183], v[116:119]
	v_mfma_f32_16x16x32_bf16 v[108:111], v[156:159], v[180:183], v[108:111]
	v_mfma_f32_16x16x32_bf16 v[108:111], v[152:155], v[160:163], v[108:111]
	v_mfma_f32_16x16x32_bf16 v[92:95], v[152:155], v[164:167], v[92:95]
	v_mfma_f32_16x16x32_bf16 v[92:95], v[156:159], v[202:205], v[92:95]
	v_mfma_f32_16x16x32_bf16 v[100:103], v[148:151], v[202:205], v[100:103]
	v_mfma_f32_16x16x32_bf16 v[100:103], v[144:147], v[164:167], v[100:103]
	v_mfma_f32_16x16x32_bf16 v[84:87], v[144:147], v[206:209], v[84:87]
	v_mfma_f32_16x16x32_bf16 v[84:87], v[148:151], v[214:217], v[84:87]
	v_mfma_f32_16x16x32_bf16 v[76:79], v[156:159], v[214:217], v[76:79]
	v_mfma_f32_16x16x32_bf16 v[76:79], v[152:155], v[206:209], v[76:79]
	v_mfma_f32_16x16x32_bf16 v[60:63], v[152:155], v[210:213], v[60:63]
	v_mfma_f32_16x16x32_bf16 v[60:63], v[156:159], v[218:221], v[60:63]
	v_mfma_f32_16x16x32_bf16 v[68:71], v[148:151], v[218:221], v[68:71]
	v_mfma_f32_16x16x32_bf16 v[68:71], v[144:147], v[210:213], v[68:71]
	s_setprio 0
	s_barrier
	s_add_i32 s57, s41, s68
	s_mov_b32 m0, s57
	ds_read_b128 v[160:163], v196 offset:16384
	ds_read_b128 v[164:167], v196 offset:18432
	ds_read_b128 v[180:183], v197 offset:16384
	ds_read_b128 v[202:205], v197 offset:18432
	ds_read_b128 v[206:209], v196 offset:20480
	ds_read_b128 v[210:213], v196 offset:22528
	ds_read_b128 v[214:217], v197 offset:20480
	ds_read_b128 v[218:221], v197 offset:22528
	global_load_lds_dwordx4 v170, s[24:25]
	s_add_i32 m0, s57, 0x2000
	s_add_u32 s58, s24, 0x2b0000
	s_addc_u32 s59, s25, 0
	s_add_i32 s57, s42, s68
	global_load_lds_dwordx4 v174, s[24:25]
	s_mov_b32 m0, s57
	s_nop 0
	global_load_lds_dwordx4 v170, s[58:59]
	s_add_i32 m0, s57, 0x2000
	s_nop 0
	global_load_lds_dwordx4 v174, s[58:59]
	s_mov_b32 m0, s34
	s_nop 0
	s_add_u32 s100, s26, 0x80
	s_addc_u32 s101, s27, 0
	global_load_lds_dwordx4 v168, s[26:27]
	s_mov_b32 m0, s35
	s_nop 0
	global_load_lds_dwordx4 v172, s[26:27]
	s_waitcnt vmcnt(8)
	s_waitcnt lgkmcnt(0)
	s_waitcnt lgkmcnt(0)
	v_mfma_f32_16x16x32_bf16 v[52:55], v[128:131], v[160:163], v[52:55]
	v_mfma_f32_16x16x32_bf16 v[52:55], v[132:135], v[180:183], v[52:55]
	v_mfma_f32_16x16x32_bf16 v[48:51], v[140:143], v[180:183], v[48:51]
	v_mfma_f32_16x16x32_bf16 v[48:51], v[136:139], v[160:163], v[48:51]
	s_barrier
	s_setprio 3
	v_mfma_f32_16x16x32_bf16 v[32:35], v[136:139], v[164:167], v[32:35]
	v_mfma_f32_16x16x32_bf16 v[32:35], v[140:143], v[202:205], v[32:35]
	v_mfma_f32_16x16x32_bf16 v[36:39], v[132:135], v[202:205], v[36:39]
	v_mfma_f32_16x16x32_bf16 v[36:39], v[128:131], v[164:167], v[36:39]
	v_mfma_f32_16x16x32_bf16 v[20:23], v[128:131], v[206:209], v[20:23]
	v_mfma_f32_16x16x32_bf16 v[20:23], v[132:135], v[214:217], v[20:23]
	v_mfma_f32_16x16x32_bf16 v[8:11], v[140:143], v[214:217], v[8:11]
	v_mfma_f32_16x16x32_bf16 v[8:11], v[136:139], v[206:209], v[8:11]
	v_mfma_f32_16x16x32_bf16 v[0:3], v[136:139], v[210:213], v[0:3]
	v_mfma_f32_16x16x32_bf16 v[0:3], v[140:143], v[218:221], v[0:3]
	v_mfma_f32_16x16x32_bf16 v[4:7], v[132:135], v[218:221], v[4:7]
	v_mfma_f32_16x16x32_bf16 v[4:7], v[128:131], v[210:213], v[4:7]
	s_setprio 0
	s_setprio 3
	v_mfma_f32_16x16x32_bf16 v[64:67], v[144:147], v[160:163], v[64:67]
	v_mfma_f32_16x16x32_bf16 v[64:67], v[148:151], v[180:183], v[64:67]
	v_mfma_f32_16x16x32_bf16 v[56:59], v[156:159], v[180:183], v[56:59]
	v_mfma_f32_16x16x32_bf16 v[56:59], v[152:155], v[160:163], v[56:59]
	v_mfma_f32_16x16x32_bf16 v[40:43], v[152:155], v[164:167], v[40:43]
	v_mfma_f32_16x16x32_bf16 v[40:43], v[156:159], v[202:205], v[40:43]
	v_mfma_f32_16x16x32_bf16 v[44:47], v[148:151], v[202:205], v[44:47]
	v_mfma_f32_16x16x32_bf16 v[44:47], v[144:147], v[164:167], v[44:47]
	v_mfma_f32_16x16x32_bf16 v[28:31], v[144:147], v[206:209], v[28:31]
	v_mfma_f32_16x16x32_bf16 v[28:31], v[148:151], v[214:217], v[28:31]
	v_mfma_f32_16x16x32_bf16 v[24:27], v[156:159], v[214:217], v[24:27]
	v_mfma_f32_16x16x32_bf16 v[24:27], v[152:155], v[206:209], v[24:27]
	v_mfma_f32_16x16x32_bf16 v[12:15], v[152:155], v[210:213], v[12:15]
	v_mfma_f32_16x16x32_bf16 v[12:15], v[156:159], v[218:221], v[12:15]
	v_mfma_f32_16x16x32_bf16 v[16:19], v[148:151], v[218:221], v[16:19]
	v_mfma_f32_16x16x32_bf16 v[16:19], v[144:147], v[210:213], v[16:19]
	s_setprio 0
	s_barrier
; #define PG8_STAGE(bufoff, gbase, voff) do { _Pragma("unroll") for (int _i = 0; _i < 2; ++_i) \
;         __builtin_amdgcn_global_load_lds((const unsigned*)((const char*)(gbase) + (voff)[_i]), (LAS unsigned*)(lds + (bufoff) + ldsw + _i * 8192), 16, 0, 0); } while (0)
; #define PG8_LDA(dst, b, h) do { _Pragma("unroll") for (int m = 0; m < 4; ++m) _Pragma("unroll") for (int k = 0; k < 2; ++k) dst[m][k] = *(const LAS bf16x8*)(lds + PG8_SA(b, h) + aoffk[k] + m * 2048); } while (0)
; #define PG8_LDB(dst, b, h) do { _Pragma("unroll") for (int n = 0; n < 2; ++n) _Pragma("unroll") for (int k = 0; k < 2; ++k) dst[n][k] = *(const LAS bf16x8*)(lds + PG8_SB(b, h) + boffk[k] + n * 2048); } while (0)
; #define PG8_WAIT_V(n) asm volatile("s_waitcnt vmcnt(" #n ")" ::: "memory")
; #define PG8_WAIT_L(n) asm volatile("s_waitcnt lgkmcnt(" #n ")" ::: "memory")
; #define PG8_BAR __builtin_amdgcn_s_barrier()
; #define PG8_SCHED __builtin_amdgcn_sched_barrier(0)
; template <class Epi, class Sched, class GemmT>
; __device__ __forceinline__ void gemm_phase(LAS unsigned char* lds, const GemmT& g, const Sched& S, const Epi& E, const int wid) {
;     ...
;                 PG8_LDB(B0, 1, 0); PG8_LDB(B1, 1, 1); PG8_SCHED; PG8_LDA(At, 1, 0); PG8_STAGE(PG8_SA(0, 1), a2 + hA2, vA2);
;                 PG8_WAIT_V(8); PG8_WAIT_L(0); PG8_BAR; PG8_MMA(0, 0, At, B0); PG8_MMA(0, 1, At, B1); PG8_BAR; PG8_SCHED;
;                 PG8_LDA(At, 1, 1); PG8_STAGE(PG8_SB(1, 0), b3, vB2); PG8_STAGE(PG8_SB(1, 1), b3 + hB2, vB2); PG8_STAGE(PG8_SA(1, 0), a3, vA2);
;                 PG8_WAIT_V(8); PG8_WAIT_L(0); PG8_BAR; PG8_MMA(1, 0, At, B0); PG8_MMA(1, 1, At, B1); PG8_BAR; PG8_SCHED;
;             }
	s_add_i32 s57, 0, 0x18000
	s_add_i32 s58, 0, 0x1c000
	ds_read_b128 v[128:131], v222
	ds_read_b128 v[132:135], v223
	ds_read_b128 v[136:139], v198
	ds_read_b128 v[140:143], v199
	ds_read_b128 v[144:147], v224
	ds_read_b128 v[148:151], v225
	ds_read_b128 v[152:155], v200
	ds_read_b128 v[156:159], v201
	s_add_u32 s26, s26, 0x2b0000
	s_addc_u32 s27, s27, 0
	s_mov_b32 m0, s36
	ds_read_b128 v[160:163], v196 offset:32768
	ds_read_b128 v[164:167], v196 offset:34816
	ds_read_b128 v[180:183], v197 offset:32768
	ds_read_b128 v[202:205], v197 offset:34816
	ds_read_b128 v[206:209], v196 offset:36864
	ds_read_b128 v[210:213], v196 offset:38912
	ds_read_b128 v[214:217], v197 offset:36864
	ds_read_b128 v[218:221], v197 offset:38912
	global_load_lds_dwordx4 v168, s[26:27]
	s_mov_b32 m0, s37
	s_nop 0
	global_load_lds_dwordx4 v172, s[26:27]
	s_waitcnt vmcnt(8)
	s_waitcnt lgkmcnt(0)
	s_waitcnt lgkmcnt(0)
	v_mfma_f32_16x16x32_bf16 v[124:127], v[128:131], v[160:163], v[124:127]
	v_mfma_f32_16x16x32_bf16 v[124:127], v[132:135], v[180:183], v[124:127]
	v_mfma_f32_16x16x32_bf16 v[120:123], v[140:143], v[180:183], v[120:123]
	v_mfma_f32_16x16x32_bf16 v[120:123], v[136:139], v[160:163], v[120:123]
	s_barrier
	s_setprio 3
	v_mfma_f32_16x16x32_bf16 v[104:107], v[136:139], v[164:167], v[104:107]
	v_mfma_f32_16x16x32_bf16 v[104:107], v[140:143], v[202:205], v[104:107]
	v_mfma_f32_16x16x32_bf16 v[112:115], v[132:135], v[202:205], v[112:115]
	v_mfma_f32_16x16x32_bf16 v[112:115], v[128:131], v[164:167], v[112:115]
	v_mfma_f32_16x16x32_bf16 v[96:99], v[128:131], v[206:209], v[96:99]
	v_mfma_f32_16x16x32_bf16 v[96:99], v[132:135], v[214:217], v[96:99]
	v_mfma_f32_16x16x32_bf16 v[88:91], v[140:143], v[214:217], v[88:91]
	v_mfma_f32_16x16x32_bf16 v[88:91], v[136:139], v[206:209], v[88:91]
	v_mfma_f32_16x16x32_bf16 v[72:75], v[136:139], v[210:213], v[72:75]
	v_mfma_f32_16x16x32_bf16 v[72:75], v[140:143], v[218:221], v[72:75]
	v_mfma_f32_16x16x32_bf16 v[80:83], v[132:135], v[218:221], v[80:83]
	v_mfma_f32_16x16x32_bf16 v[80:83], v[128:131], v[210:213], v[80:83]
	s_setprio 0
	s_setprio 3
	v_mfma_f32_16x16x32_bf16 v[116:119], v[144:147], v[160:163], v[116:119]
	v_mfma_f32_16x16x32_bf16 v[116:119], v[148:151], v[180:183], v[116:119]
	v_mfma_f32_16x16x32_bf16 v[108:111], v[156:159], v[180:183], v[108:111]
	v_mfma_f32_16x16x32_bf16 v[108:111], v[152:155], v[160:163], v[108:111]
	v_mfma_f32_16x16x32_bf16 v[92:95], v[152:155], v[164:167], v[92:95]
	v_mfma_f32_16x16x32_bf16 v[92:95], v[156:159], v[202:205], v[92:95]
	v_mfma_f32_16x16x32_bf16 v[100:103], v[148:151], v[202:205], v[100:103]
	v_mfma_f32_16x16x32_bf16 v[100:103], v[144:147], v[164:167], v[100:103]
	v_mfma_f32_16x16x32_bf16 v[84:87], v[144:147], v[206:209], v[84:87]
	v_mfma_f32_16x16x32_bf16 v[84:87], v[148:151], v[214:217], v[84:87]
	v_mfma_f32_16x16x32_bf16 v[76:79], v[156:159], v[214:217], v[76:79]
	v_mfma_f32_16x16x32_bf16 v[76:79], v[152:155], v[206:209], v[76:79]
	v_mfma_f32_16x16x32_bf16 v[60:63], v[152:155], v[210:213], v[60:63]
	v_mfma_f32_16x16x32_bf16 v[60:63], v[156:159], v[218:221], v[60:63]
	v_mfma_f32_16x16x32_bf16 v[68:71], v[148:151], v[218:221], v[68:71]
	v_mfma_f32_16x16x32_bf16 v[68:71], v[144:147], v[210:213], v[68:71]
	s_setprio 0
	s_barrier
	s_add_i32 s26, s57, s68
	s_mov_b32 m0, s26
	ds_read_b128 v[160:163], v196 offset:49152
	ds_read_b128 v[164:167], v196 offset:51200
	ds_read_b128 v[180:183], v197 offset:49152
	ds_read_b128 v[202:205], v197 offset:51200
	ds_read_b128 v[206:209], v196 offset:53248
	ds_read_b128 v[210:213], v196 offset:55296
	ds_read_b128 v[214:217], v197 offset:53248
	ds_read_b128 v[218:221], v197 offset:55296
	s_add_u32 s98, s24, 0x80
	s_addc_u32 s99, s25, 0
	s_nop 0
	global_load_lds_dwordx4 v170, s[98:99]
	s_add_i32 m0, s26, 0x2000
	s_add_u32 s24, s24, 0x2b0080
	s_addc_u32 s25, s25, 0
	s_add_i32 s26, s58, s68
	global_load_lds_dwordx4 v174, s[98:99]
	s_mov_b32 m0, s26
	s_nop 0
	global_load_lds_dwordx4 v170, s[24:25]
	s_add_i32 m0, s26, 0x2000
	s_nop 0
	global_load_lds_dwordx4 v174, s[24:25]
	s_mov_b32 m0, s39
	s_nop 0
	global_load_lds_dwordx4 v168, s[100:101]
	s_mov_b32 m0, s40
	s_nop 0
	global_load_lds_dwordx4 v172, s[100:101]
	s_waitcnt vmcnt(8)
	s_waitcnt lgkmcnt(0)
	s_waitcnt lgkmcnt(0)
	v_mfma_f32_16x16x32_bf16 v[52:55], v[128:131], v[160:163], v[52:55]
	v_mfma_f32_16x16x32_bf16 v[52:55], v[132:135], v[180:183], v[52:55]
	v_mfma_f32_16x16x32_bf16 v[48:51], v[140:143], v[180:183], v[48:51]
	v_mfma_f32_16x16x32_bf16 v[48:51], v[136:139], v[160:163], v[48:51]
	s_barrier
	s_setprio 3
	v_mfma_f32_16x16x32_bf16 v[32:35], v[136:139], v[164:167], v[32:35]
	v_mfma_f32_16x16x32_bf16 v[32:35], v[140:143], v[202:205], v[32:35]
	v_mfma_f32_16x16x32_bf16 v[36:39], v[132:135], v[202:205], v[36:39]
	v_mfma_f32_16x16x32_bf16 v[36:39], v[128:131], v[164:167], v[36:39]
	v_mfma_f32_16x16x32_bf16 v[20:23], v[128:131], v[206:209], v[20:23]
	v_mfma_f32_16x16x32_bf16 v[20:23], v[132:135], v[214:217], v[20:23]
	v_mfma_f32_16x16x32_bf16 v[8:11], v[140:143], v[214:217], v[8:11]
	v_mfma_f32_16x16x32_bf16 v[8:11], v[136:139], v[206:209], v[8:11]
	v_mfma_f32_16x16x32_bf16 v[0:3], v[136:139], v[210:213], v[0:3]
	v_mfma_f32_16x16x32_bf16 v[0:3], v[140:143], v[218:221], v[0:3]
	v_mfma_f32_16x16x32_bf16 v[4:7], v[132:135], v[218:221], v[4:7]
	v_mfma_f32_16x16x32_bf16 v[4:7], v[128:131], v[210:213], v[4:7]
	s_setprio 0
	s_setprio 3
	v_mfma_f32_16x16x32_bf16 v[64:67], v[144:147], v[160:163], v[64:67]
	v_mfma_f32_16x16x32_bf16 v[64:67], v[148:151], v[180:183], v[64:67]
	v_mfma_f32_16x16x32_bf16 v[56:59], v[156:159], v[180:183], v[56:59]
	v_mfma_f32_16x16x32_bf16 v[56:59], v[152:155], v[160:163], v[56:59]
	v_mfma_f32_16x16x32_bf16 v[40:43], v[152:155], v[164:167], v[40:43]
	v_mfma_f32_16x16x32_bf16 v[40:43], v[156:159], v[202:205], v[40:43]
	v_mfma_f32_16x16x32_bf16 v[44:47], v[148:151], v[202:205], v[44:47]
	v_mfma_f32_16x16x32_bf16 v[44:47], v[144:147], v[164:167], v[44:47]
	v_mfma_f32_16x16x32_bf16 v[28:31], v[144:147], v[206:209], v[28:31]
	v_mfma_f32_16x16x32_bf16 v[28:31], v[148:151], v[214:217], v[28:31]
	v_mfma_f32_16x16x32_bf16 v[24:27], v[156:159], v[214:217], v[24:27]
	v_mfma_f32_16x16x32_bf16 v[24:27], v[152:155], v[206:209], v[24:27]
	v_mfma_f32_16x16x32_bf16 v[12:15], v[152:155], v[210:213], v[12:15]
	v_mfma_f32_16x16x32_bf16 v[12:15], v[156:159], v[218:221], v[12:15]
	v_mfma_f32_16x16x32_bf16 v[16:19], v[148:151], v[218:221], v[16:19]
	v_mfma_f32_16x16x32_bf16 v[16:19], v[144:147], v[210:213], v[16:19]
	s_setprio 0
	s_barrier
	s_add_i32 s56, s56, 2
	s_add_u32 s22, s22, 0x100
	s_addc_u32 s23, s23, 0
	s_add_u32 s54, s54, 0x100
	s_addc_u32 s55, s55, 0
	s_cmpk_gt_u32 s56, 0xa9
	s_cbranch_scc0 .LBB0_1096
	s_and_b64 vcc, exec, s[8:9]
	s_cbranch_vccz .LBB0_1099
	s_barrier
